# v011 + nt on phase-2 loads and phase-5 loads/stores
# baseline (speedup 1.0000x reference)
; template <bool FULL> __device__ __forceinline__ void hg_load(const HgCtx& c, HgPref& r, int n) {
;     const size_t o = (size_t)n * 16 * 8192;
;     if (FULL) { r.q[0] = *(const u32x4*)(c.QI + o); r.q[1] = *(const u32x4*)(c.QI + o + 4096); }
;     r.k[0] = *(const u32x4*)(c.KI + o); r.k[1] = *(const u32x4*)(c.KI + o + 4096);
;     r.v[0] = *(const u32x4*)(c.VI + o); r.v[1] = *(const u32x4*)(c.VI + o + 4096); if (c.tid < 96) r.s = *(const u32x4*)(c.SCLG + (size_t)n * 16 * 384);
; }
; template <bool FULL> __device__ __forceinline__ void hg_store(const HgCtx& c, const HgPref& r, LAS unsigned char* b) {
;     if (FULL) { *(LAS u32x4*)(b + HB_Q + c.loff0) = r.q[0]; *(LAS u32x4*)(b + HB_Q + c.loff1) = r.q[1]; }
;     *(LAS u32x4*)(b + HB_K + c.loff0) = r.k[0]; *(LAS u32x4*)(b + HB_K + c.loff1) = r.k[1];
;     *(LAS u32x4*)(b + HB_V + c.loff0) = r.v[0]; *(LAS u32x4*)(b + HB_V + c.loff1) = r.v[1]; if (c.tid < 96) *(LAS u32x4*)(b + HB_S + c.tid * 16) = r.s;
; }
; template <bool FULL> __device__ __forceinline__ void hgrn_scan(const Args& a, LAS unsigned char* lds, int item) {
;     HgCtx c;
;     c.tid = threadIdx.x; const int l = c.tid & 63; c.w = __builtin_amdgcn_readfirstlane(c.tid >> 6); c.fr = l & 15; c.fq = l >> 4; c.q4 = (l & 15) >> 2; c.p4 = l & 3;
;     const int seg = item & 3, bh = item >> 2, b = bh >> 4, h = bh & 15;
;     const size_t cb0 = (size_t)(b * 64) * 16 + h;
;     c.QI = (const bf16_t*)(a.ws + WS_QI) + cb0 * 8192 + c.tid * 8;
;     c.KI = (const bf16_t*)(a.ws + WS_KI) + cb0 * 8192 + c.tid * 8;
;     c.VI = (const bf16_t*)(a.ws + WS_VI) + cb0 * 8192 + c.tid * 8;
;     c.GZ = (const bf16_t*)(a.ws + WS_GZ) + cb0 * 8192 + c.fr * 128 + 16 * c.w + 4 * c.fq;
;     c.SCLG = (const float*)(a.ws + WS_SCL) + cb0 * 384 + c.tid * 4;
;     c.H = (bf16_t*)(a.ws + WS_H); c.hrow = b * SEQ + c.fr; c.hcol = BW + h * 128 + 16 * c.w + 4 * c.fq;
;     c.loff0 = (c.tid >> 4) * HP + (c.tid & 15) * 16; c.loff1 = c.loff0 + 32 * HP;
;     c.lds = lds;
;     c.nw4 = *(const f32x4*)(a.hg_nw + h * 128 + 16 * c.w + 4 * c.fq);
;     float* SL = (float*)(a.ws + WS_SL);
;     const int n0 = seg * HG_SEGLEN;
;     HgPref P;
;     hg_load<FULL>(c, P, n0);
;     f32x4 S[8];
; #pragma unroll
;     for (int dt = 0; dt < 8; ++dt) S[dt] = (f32x4){0.f, 0.f, 0.f, 0.f};
;     if (FULL && seg > 0) {
;         LAS float* DT = (LAS float*)(lds + HL_SC);
;         if (c.tid < 128) {
.LBB0_258:
	s_cmp_lt_i32 s90, 3
	s_cselect_b64 s[4:5], -1, 0
	s_waitcnt lgkmcnt(0)
	s_and_b64 s[38:39], s[4:5], s[0:1]
	s_andn2_b64 vcc, exec, s[38:39]
	s_cbranch_vccnz .LBB0_379
	s_and_b32 s3, s2, 3
	s_cmp_eq_u32 s3, 3
	s_cbranch_scc1 .LBB0_276
	s_and_b32 s8, s2, 0xffffffc0
	s_ashr_i32 s12, s2, 2
	s_ashr_i32 s9, s8, 31
	s_and_b32 s14, s12, 15
	s_lshl_b64 s[0:1], s[8:9], 4
	s_or_b32 s0, s0, s14
	s_lshl_b64 s[4:5], s[0:1], 14
	s_add_u32 s4, s30, s4
	s_addc_u32 s5, s31, s5
	v_lshlrev_b32_e32 v168, 4, v210
	v_mov_b32_e32 v169, 0
	v_lshl_add_u64 v[0:1], s[4:5], 0, v[168:169]
	s_mov_b64 s[4:5], 0x24700000
	v_lshl_add_u64 v[20:21], v[0:1], 0, s[4:5]
	s_mov_b64 s[4:5], 0x28700000
	v_lshl_add_u64 v[28:29], v[0:1], 0, s[4:5]
	s_mulk_i32 s1, 0x600
	s_mul_hi_u32 s4, s0, 0x600
	s_add_i32 s4, s4, s1
	s_mulk_i32 s0, 0x600
	s_add_u32 s0, s30, s0
	s_mov_b32 s11, 0
	s_addc_u32 s1, s31, s4
	s_lshl_b32 s10, s3, 22
	v_lshl_add_u64 v[0:1], v[20:21], 0, s[10:11]
	s_movk_i32 s4, 0x2000
	v_add_co_u32_e32 v2, vcc, s4, v0
	v_readfirstlane_b32 s13, v210
	s_nop 0
	v_addc_co_u32_e32 v3, vcc, 0, v1, vcc
	global_load_dwordx4 v[4:7], v[0:1], off nt
	global_load_dwordx4 v[8:11], v[2:3], off nt
	v_lshl_add_u64 v[0:1], v[28:29], 0, s[10:11]
	v_add_co_u32_e32 v2, vcc, 0x2000, v0
	s_lshl_b32 s6, s3, 4
	s_nop 0
	v_addc_co_u32_e32 v3, vcc, 0, v1, vcc
	global_load_dwordx4 v[12:15], v[0:1], off nt
	global_load_dwordx4 v[16:19], v[2:3], off nt
	v_lshl_add_u64 v[0:1], s[0:1], 0, v[168:169]
	s_mov_b64 s[0:1], 0x49300000
	v_lshl_add_u64 v[40:41], v[0:1], 0, s[0:1]
	s_movk_i32 s0, 0x60
	v_cmp_gt_u32_e64 s[0:1], s0, v210
	s_and_saveexec_b64 s[4:5], s[0:1]
	s_cbranch_execz .LBB0_262
	s_mul_i32 s16, s6, 0x6000
	s_mov_b32 s17, s11
	v_lshl_add_u64 v[0:1], v[40:41], 0, s[16:17]
	global_load_dwordx4 v[0:3], v[0:1], off nt
.LBB0_262:
	s_or_b64 exec, exec, s[4:5]
	v_lshrrev_b32_e32 v22, 4, v210
	v_and_b32_e32 v23, 0xf0, v168
	s_movk_i32 s4, 0x110
	v_mad_u32_u24 v177, v22, s4, v23
	v_add_u32_e32 v175, 0, v177
	v_add_u32_e32 v174, 0, v168
	s_waitcnt vmcnt(0)
	ds_write_b128 v175, v[4:7] offset:17408
	ds_write_b128 v175, v[8:11] offset:26112
	ds_write_b128 v175, v[12:15] offset:34816
	ds_write_b128 v175, v[16:19] offset:43520
	s_and_saveexec_b64 s[4:5], s[0:1]
	ds_write_b128 v174, v[0:3] offset:52224
	s_or_b64 exec, exec, s[4:5]
	s_or_b32 s11, s6, 1
	s_lshl_b32 s4, s11, 18
	s_mov_b32 s5, 0
	v_lshl_add_u64 v[4:5], v[20:21], 0, s[4:5]
	v_add_co_u32_e32 v6, vcc, 0x2000, v4
	v_mov_b64_e32 v[38:39], v[2:3]
	s_nop 0
	v_addc_co_u32_e32 v7, vcc, 0, v5, vcc
	global_load_dwordx4 v[20:23], v[4:5], off nt
	global_load_dwordx4 v[24:27], v[6:7], off nt
	v_lshl_add_u64 v[4:5], v[28:29], 0, s[4:5]
	v_add_co_u32_e32 v6, vcc, 0x2000, v4
	v_mov_b64_e32 v[36:37], v[0:1]
	s_nop 0
	v_addc_co_u32_e32 v7, vcc, 0, v5, vcc
	global_load_dwordx4 v[28:31], v[4:5], off nt
	global_load_dwordx4 v[32:35], v[6:7], off nt
	s_and_saveexec_b64 s[6:7], s[0:1]
	s_cbranch_execz .LBB0_266
	s_mul_i32 s16, s11, 0x6000
	s_mov_b32 s17, 0
	v_lshl_add_u64 v[4:5], v[40:41], 0, s[16:17]
	global_load_dwordx4 v[36:39], v[4:5], off nt

; template <bool FULL> __device__ __forceinline__ void hg_load(const HgCtx& c, HgPref& r, int n) {
;     const size_t o = (size_t)n * 16 * 8192;
;     if (FULL) { r.q[0] = *(const u32x4*)(c.QI + o); r.q[1] = *(const u32x4*)(c.QI + o + 4096); }
;     r.k[0] = *(const u32x4*)(c.KI + o); r.k[1] = *(const u32x4*)(c.KI + o + 4096);
;     r.v[0] = *(const u32x4*)(c.VI + o); r.v[1] = *(const u32x4*)(c.VI + o + 4096); if (c.tid < 96) r.s = *(const u32x4*)(c.SCLG + (size_t)n * 16 * 384);
; }
; template <bool FULL, bool DEEP> __device__ __forceinline__ void hg_step(const HgCtx& c, int n, int i, int len, HgPref& P, HgPref& PN, f32x4 (&S)[8]) {
;     ...
;     if (DEEP) { if (i + 2 < len) hg_load<FULL>(c, PN, n + 2); }
.LBB0_267:
	v_lshl_add_u64 v[12:13], s[8:9], 0, v[168:169]
	v_add_co_u32_e32 v14, vcc, s14, v12
	s_waitcnt lgkmcnt(0)
	s_nop 0
	v_addc_co_u32_e32 v15, vcc, 0, v13, vcc
	v_add_co_u32_e32 v16, vcc, 0x24782000, v12
	s_barrier
	s_nop 0
	v_addc_co_u32_e32 v17, vcc, 0, v13, vcc
	v_add_co_u32_e32 v40, vcc, 0x28780000, v12
	s_nop 1
	v_addc_co_u32_e32 v41, vcc, 0, v13, vcc
	v_add_co_u32_e32 v42, vcc, 0x28782000, v12
	global_load_dwordx4 v[4:7], v[14:15], off nt
	global_load_dwordx4 v[8:11], v[16:17], off nt
	v_addc_co_u32_e32 v43, vcc, 0, v13, vcc
	global_load_dwordx4 v[12:15], v[40:41], off nt
	global_load_dwordx4 v[16:19], v[42:43], off nt
	s_and_saveexec_b64 s[10:11], s[0:1]
	s_cbranch_execz .LBB0_269
	v_lshl_add_u64 v[0:1], s[6:7], 0, v[168:169]
	global_load_dwordx4 v[0:3], v[0:1], off nt

; #define LAS __attribute__((address_space(3)))
; template <bool FULL> __device__ __forceinline__ void hgrn_scan(const Args& a, LAS unsigned char* lds, int item) {
;     HgCtx c;
;     c.tid = threadIdx.x; const int l = c.tid & 63; c.w = __builtin_amdgcn_readfirstlane(c.tid >> 6); c.fr = l & 15; c.fq = l >> 4; c.q4 = (l & 15) >> 2; c.p4 = l & 3;
;     const int seg = item & 3, bh = item >> 2, b = bh >> 4, h = bh & 15;
;     const size_t cb0 = (size_t)(b * 64) * 16 + h;
;     c.QI = (const bf16_t*)(a.ws + WS_QI) + cb0 * 8192 + c.tid * 8;
;     c.KI = (const bf16_t*)(a.ws + WS_KI) + cb0 * 8192 + c.tid * 8;
;     c.VI = (const bf16_t*)(a.ws + WS_VI) + cb0 * 8192 + c.tid * 8;
;     c.GZ = (const bf16_t*)(a.ws + WS_GZ) + cb0 * 8192 + c.fr * 128 + 16 * c.w + 4 * c.fq;
;     c.SCLG = (const float*)(a.ws + WS_SCL) + cb0 * 384 + c.tid * 4;
;     c.H = (bf16_t*)(a.ws + WS_H); c.hrow = b * SEQ + c.fr; c.hcol = BW + h * 128 + 16 * c.w + 4 * c.fq;
;     c.loff0 = (c.tid >> 4) * HP + (c.tid & 15) * 16; c.loff1 = c.loff0 + 32 * HP;
;     c.lds = lds;
;     c.nw4 = *(const f32x4*)(a.hg_nw + h * 128 + 16 * c.w + 4 * c.fq);
;     float* SL = (float*)(a.ws + WS_SL);
;     const int n0 = seg * HG_SEGLEN;
;     HgPref P;
;     hg_load<FULL>(c, P, n0);
.LBB0_328:
	s_or_b64 exec, exec, s[0:1]
	s_and_b32 s22, s2, 0xffffffc0
	s_ashr_i32 s10, s2, 2
	s_ashr_i32 s23, s22, 31
	s_and_b32 s53, s10, 15
	s_lshl_b64 s[4:5], s[22:23], 4
	v_readfirstlane_b32 s52, v210
	s_or_b32 s4, s4, s53
	s_lshr_b32 s54, s52, 6
	s_lshl_b64 s[0:1], s[4:5], 14
	v_mov_b32_e32 v159, 0
	s_add_u32 s0, s30, s0
	v_readlane_b32 s12, v252, 0
	v_lshlrev_b32_e32 v160, 4, v210
	v_mov_b32_e32 v161, v159
	s_addc_u32 s1, s31, s1
	v_readlane_b32 s13, v252, 1
	v_lshl_add_u64 v[4:5], s[0:1], 0, v[160:161]
	s_lshl_b32 s0, s53, 9
	s_mov_b64 s[8:9], s[12:13]
	s_add_u32 s0, s8, s0
	s_addc_u32 s1, s9, 0
	s_and_b32 s6, s52, 0xffffffc0
	s_add_u32 s0, s0, s6
	s_mov_b32 s25, 0
	s_addc_u32 s1, s1, 0
	v_and_b32_e32 v214, 48, v210
	s_lshl_b32 s24, s3, 22
	s_waitcnt lgkmcnt(0)
	s_barrier
	global_load_dwordx4 v[0:3], v214, s[0:1] nt
	v_lshl_add_u64 v[4:5], v[4:5], 0, s[24:25]
	s_mov_b32 s0, 0x20700000
	v_add_co_u32_e32 v6, vcc, s0, v4
	s_mov_b32 s0, 0x20702000
	s_nop 0
	v_addc_co_u32_e32 v7, vcc, 0, v5, vcc
	v_add_co_u32_e32 v16, vcc, s0, v4
	s_mov_b32 s0, 0x24700000
	s_nop 0
	v_addc_co_u32_e32 v17, vcc, 0, v5, vcc
	global_load_dwordx4 v[8:11], v[6:7], off nt
	global_load_dwordx4 v[12:15], v[16:17], off nt
	v_add_co_u32_e32 v6, vcc, s0, v4
	s_mov_b32 s0, 0x24702000
	s_nop 0
	v_addc_co_u32_e32 v7, vcc, 0, v5, vcc
	v_add_co_u32_e32 v24, vcc, s0, v4
	s_movk_i32 s0, 0x60
	s_nop 0
	v_addc_co_u32_e32 v25, vcc, 0, v5, vcc
	global_load_dwordx4 v[16:19], v[6:7], off nt
	global_load_dwordx4 v[20:23], v[24:25], off nt
	v_add_co_u32_e32 v6, vcc, 0x28700000, v4
	v_bfe_u32 v211, v210, 4, 2
	s_nop 0
	v_addc_co_u32_e32 v7, vcc, 0, v5, vcc
	v_add_co_u32_e32 v4, vcc, 0x28702000, v4
	v_lshlrev_b32_e32 v158, 2, v210
	s_nop 0
	v_addc_co_u32_e32 v5, vcc, 0, v5, vcc
	global_load_dwordx4 v[24:27], v[6:7], off nt
	global_load_dwordx4 v[28:31], v[4:5], off nt
	s_lshl_b32 s34, s3, 4
	v_cmp_gt_u32_e64 s[0:1], s0, v210
	v_readlane_b32 s14, v252, 2
	v_readlane_b32 s15, v252, 3
	v_readlane_b32 s16, v252, 4
	v_readlane_b32 s17, v252, 5
	v_readlane_b32 s18, v252, 6
	v_readlane_b32 s19, v252, 7
	s_and_saveexec_b64 s[6:7], s[0:1]
	s_cbranch_execz .LBB0_330
	s_mul_i32 s8, s5, 0x600
	s_mul_hi_u32 s9, s4, 0x600
	s_add_i32 s9, s9, s8
	s_mul_i32 s8, s4, 0x600
	s_add_u32 s8, s30, s8
	s_addc_u32 s9, s31, s9
	v_lshlrev_b32_e32 v4, 2, v158
	v_mov_b32_e32 v5, 0
	v_lshl_add_u64 v[4:5], s[8:9], 0, v[4:5]
	s_mul_i32 s8, s34, 0x6000
	s_mov_b32 s9, s25
	v_lshl_add_u64 v[4:5], v[4:5], 0, s[8:9]
	v_add_co_u32_e32 v4, vcc, 0x49300000, v4
	s_nop 1
	v_addc_co_u32_e32 v5, vcc, 0, v5, vcc
	global_load_dwordx4 v[4:7], v[4:5], off nt

; template <bool FULL> __device__ __forceinline__ void hgrn_scan(const Args& a, LAS unsigned char* lds, int item) {
;     ...
;         if (c.tid < 128) {
;             const float* ep = (const float*)(a.ws + WS_SCL) + cb0 * 384 + 128 + c.tid;
;             for (int sp = 0; sp < seg; ++sp) { float d = 1.f;
;                 for (int k = 0; k < HG_SEGLEN; ++k) d *= ep[(size_t)(sp * HG_SEGLEN + k) * 16 * 384];
;                 DT[sp * 128 + c.tid] = d; }
.LBB0_333:
	v_lshl_add_u64 v[36:37], v[32:33], 0, s[8:9]
	v_add_co_u32_e32 v38, vcc, 0x49300000, v36
	s_add_u32 s8, s8, 0x60000
	s_nop 0
	v_addc_co_u32_e32 v39, vcc, 0, v37, vcc
	v_add_co_u32_e32 v40, vcc, 0x49306000, v36
	s_addc_u32 s9, s9, 0
	s_nop 0
	v_addc_co_u32_e32 v41, vcc, 0, v37, vcc
	v_add_co_u32_e32 v42, vcc, 0x4930c000, v36
	global_load_dword v44, v[38:39], off offset:512 nt
	global_load_dword v45, v[40:41], off offset:512 nt
	v_addc_co_u32_e32 v43, vcc, 0, v37, vcc
	v_add_co_u32_e32 v38, vcc, 0x49312000, v36
	s_cmp_lg_u32 s11, s8
	s_nop 0
	v_addc_co_u32_e32 v39, vcc, 0, v37, vcc
	v_add_co_u32_e32 v40, vcc, 0x49318000, v36
	global_load_dword v46, v[42:43], off offset:512 nt
	global_load_dword v47, v[38:39], off offset:512 nt
	v_addc_co_u32_e32 v41, vcc, 0, v37, vcc
	v_add_co_u32_e32 v38, vcc, 0x4931e000, v36
	s_nop 1
	v_addc_co_u32_e32 v39, vcc, 0, v37, vcc
	v_add_co_u32_e32 v42, vcc, 0x49324000, v36
	global_load_dword v48, v[40:41], off offset:512 nt
	global_load_dword v49, v[38:39], off offset:512 nt
	v_addc_co_u32_e32 v43, vcc, 0, v37, vcc
	v_add_co_u32_e32 v38, vcc, 0x4932a000, v36
	s_nop 1
	v_addc_co_u32_e32 v39, vcc, 0, v37, vcc
	v_add_co_u32_e32 v40, vcc, 0x49330000, v36
	global_load_dword v50, v[42:43], off offset:512 nt
	global_load_dword v51, v[38:39], off offset:512 nt
	v_addc_co_u32_e32 v41, vcc, 0, v37, vcc
	v_add_co_u32_e32 v38, vcc, 0x49336000, v36
	s_nop 1
	v_addc_co_u32_e32 v39, vcc, 0, v37, vcc
	v_add_co_u32_e32 v42, vcc, 0x4933c000, v36
	global_load_dword v52, v[40:41], off offset:512 nt
	global_load_dword v53, v[38:39], off offset:512 nt
	v_addc_co_u32_e32 v43, vcc, 0, v37, vcc
	v_add_co_u32_e32 v38, vcc, 0x49342000, v36
	s_nop 1
	v_addc_co_u32_e32 v39, vcc, 0, v37, vcc
	v_add_co_u32_e32 v40, vcc, 0x49348000, v36
	global_load_dword v54, v[42:43], off offset:512 nt
	global_load_dword v55, v[38:39], off offset:512 nt
	v_addc_co_u32_e32 v41, vcc, 0, v37, vcc
	v_add_co_u32_e32 v38, vcc, 0x4934e000, v36
	s_nop 1
	v_addc_co_u32_e32 v39, vcc, 0, v37, vcc
	v_add_co_u32_e32 v42, vcc, 0x49354000, v36
	global_load_dword v40, v[40:41], off offset:512 nt
	s_nop 0
	global_load_dword v38, v[38:39], off offset:512 nt
	v_addc_co_u32_e32 v43, vcc, 0, v37, vcc
	v_add_co_u32_e32 v36, vcc, 0x4935a000, v36
	s_nop 1
	v_addc_co_u32_e32 v37, vcc, 0, v37, vcc
	global_load_dword v39, v[42:43], off offset:512 nt
	s_nop 0
	global_load_dword v36, v[36:37], off offset:512 nt
	s_waitcnt vmcnt(14)
	v_mul_f32_e32 v37, v44, v45
	s_waitcnt vmcnt(13)
	v_mul_f32_e32 v37, v37, v46
	s_waitcnt vmcnt(12)
	v_mul_f32_e32 v37, v37, v47
	s_waitcnt vmcnt(11)
	v_mul_f32_e32 v37, v37, v48
	s_waitcnt vmcnt(10)
	v_mul_f32_e32 v37, v37, v49
	s_waitcnt vmcnt(9)
	v_mul_f32_e32 v37, v37, v50
	s_waitcnt vmcnt(8)
	v_mul_f32_e32 v37, v37, v51
	s_waitcnt vmcnt(7)
	v_mul_f32_e32 v37, v37, v52
	s_waitcnt vmcnt(6)
	v_mul_f32_e32 v37, v37, v53
	s_waitcnt vmcnt(5)
	v_mul_f32_e32 v37, v37, v54
	s_waitcnt vmcnt(4)
	v_mul_f32_e32 v37, v37, v55
	s_waitcnt vmcnt(3)
	v_mul_f32_e32 v37, v37, v40
	s_waitcnt vmcnt(2)
	v_mul_f32_e32 v37, v37, v38
	s_waitcnt vmcnt(1)
	v_mul_f32_e32 v37, v37, v39
	s_waitcnt vmcnt(0)
	v_mul_f32_e32 v36, v37, v36
	ds_write_b32 v35, v36
	v_add_u32_e32 v35, 0x200, v35
	s_cbranch_scc1 .LBB0_333

; #define LAS __attribute__((address_space(3)))
; template <bool FULL> __device__ __forceinline__ void hgrn_scan(const Args& a, LAS unsigned char* lds, int item) {
;     ...
;         for (int sp = 0; sp < seg; ++sp) {
;             const float* lp = SL + ((size_t)(bh * 3 + sp) * 64 + c.w * 8) * 256 + l * 4;
; #pragma unroll
;             for (int dt = 0; dt < 8; ++dt) { const f32x4 dv = *(const LAS f32x4*)(DT + sp * 128 + 32 * (dt >> 1) + 8 * c.fq + 4 * (dt & 1)); S[dt] = dv * S[dt] + *(const f32x4*)(lp + dt * 256); }
;         }
.LBB0_336:
	s_add_i32 s8, s10, s6
	s_ashr_i32 s9, s8, 31
	s_add_i32 s12, s8, 1
	s_lshl_b64 s[8:9], s[8:9], 16
	s_ashr_i32 s13, s12, 31
	v_lshl_add_u64 v[54:55], v[32:33], 0, s[8:9]
	s_lshl_b64 s[8:9], s[12:13], 16
	v_add_co_u32_e32 v86, vcc, s11, v54
	v_lshl_add_u64 v[88:89], v[32:33], 0, s[8:9]
	s_nop 0
	v_addc_co_u32_e32 v87, vcc, 0, v55, vcc
	v_add_co_u32_e32 v98, vcc, s11, v88
	global_load_dwordx4 v[38:41], v[54:55], off nt
	global_load_dwordx4 v[42:45], v[54:55], off offset:1024 nt
	global_load_dwordx4 v[46:49], v[54:55], off offset:2048 nt
	global_load_dwordx4 v[50:53], v[54:55], off offset:3072 nt
	v_addc_co_u32_e32 v99, vcc, 0, v89, vcc
	global_load_dwordx4 v[54:57], v[86:87], off nt
	global_load_dwordx4 v[58:61], v[86:87], off offset:1024 nt
	global_load_dwordx4 v[62:65], v[86:87], off offset:2048 nt
	global_load_dwordx4 v[66:69], v[86:87], off offset:3072 nt
	global_load_dwordx4 v[70:73], v[88:89], off nt
	global_load_dwordx4 v[74:77], v[88:89], off offset:1024 nt
	global_load_dwordx4 v[78:81], v[88:89], off offset:2048 nt
	global_load_dwordx4 v[82:85], v[88:89], off offset:3072 nt
	s_nop 0
	global_load_dwordx4 v[86:89], v[98:99], off nt
	global_load_dwordx4 v[90:93], v[98:99], off offset:1024 nt
	global_load_dwordx4 v[94:97], v[98:99], off offset:2048 nt
	s_nop 0
	global_load_dwordx4 v[98:101], v[98:99], off offset:3072 nt
	ds_read_b128 v[102:105], v36
	ds_read_b128 v[106:109], v36 offset:16
	ds_read_b128 v[110:113], v36 offset:128
	ds_read_b128 v[114:117], v36 offset:144
	ds_read_b128 v[118:121], v36 offset:256
	ds_read_b128 v[122:125], v36 offset:272
	ds_read_b128 v[126:129], v36 offset:384
	ds_read_b128 v[130:133], v36 offset:400
	ds_read_b128 v[134:137], v36 offset:512
	ds_read_b128 v[138:141], v36 offset:528
	ds_read_b128 v[142:145], v36 offset:640
	ds_read_b128 v[146:149], v36 offset:656
	ds_read_b128 v[150:153], v36 offset:768
	ds_read_b128 v[154:157], v36 offset:784
	ds_read_b128 v[194:197], v36 offset:896
	ds_read_b128 v[198:201], v36 offset:912
	s_add_i32 s6, s6, 2
	v_add_u32_e32 v36, 0x400, v36
	s_cmp_eq_u32 s7, s6
	s_waitcnt vmcnt(11) lgkmcnt(11)
	v_pk_fma_f32 v[56:57], v[174:175], v[120:121], v[56:57]
	v_pk_fma_f32 v[40:41], v[190:191], v[104:105], v[40:41]
	v_pk_fma_f32 v[38:39], v[192:193], v[102:103], v[38:39]
	v_pk_fma_f32 v[44:45], v[186:187], v[108:109], v[44:45]
	v_pk_fma_f32 v[42:43], v[188:189], v[106:107], v[42:43]
	v_pk_fma_f32 v[48:49], v[182:183], v[112:113], v[48:49]
	v_pk_fma_f32 v[46:47], v[184:185], v[110:111], v[46:47]
	v_pk_fma_f32 v[52:53], v[178:179], v[116:117], v[52:53]
	v_pk_fma_f32 v[50:51], v[180:181], v[114:115], v[50:51]
	v_pk_fma_f32 v[54:55], v[176:177], v[118:119], v[54:55]
	s_waitcnt vmcnt(10) lgkmcnt(10)
	v_pk_fma_f32 v[60:61], v[170:171], v[124:125], v[60:61]
	v_pk_fma_f32 v[58:59], v[172:173], v[122:123], v[58:59]
	s_waitcnt vmcnt(9) lgkmcnt(9)
	v_pk_fma_f32 v[64:65], v[162:163], v[128:129], v[64:65]
	v_pk_fma_f32 v[62:63], v[168:169], v[126:127], v[62:63]
	s_waitcnt vmcnt(8) lgkmcnt(8)
	v_pk_fma_f32 v[68:69], v[166:167], v[132:133], v[68:69]
	v_pk_fma_f32 v[66:67], v[164:165], v[130:131], v[66:67]
	s_waitcnt vmcnt(7) lgkmcnt(7)
	v_pk_fma_f32 v[190:191], v[40:41], v[136:137], v[72:73]
	v_pk_fma_f32 v[192:193], v[38:39], v[134:135], v[70:71]
	s_waitcnt vmcnt(6) lgkmcnt(6)
	v_pk_fma_f32 v[186:187], v[44:45], v[140:141], v[76:77]
	v_pk_fma_f32 v[188:189], v[42:43], v[138:139], v[74:75]
	s_waitcnt vmcnt(5) lgkmcnt(5)
	v_pk_fma_f32 v[182:183], v[48:49], v[144:145], v[80:81]
	v_pk_fma_f32 v[184:185], v[46:47], v[142:143], v[78:79]
	s_waitcnt vmcnt(4) lgkmcnt(4)
	v_pk_fma_f32 v[178:179], v[52:53], v[148:149], v[84:85]
	v_pk_fma_f32 v[180:181], v[50:51], v[146:147], v[82:83]
	s_waitcnt vmcnt(3) lgkmcnt(3)
	v_pk_fma_f32 v[174:175], v[56:57], v[152:153], v[88:89]
	v_pk_fma_f32 v[176:177], v[54:55], v[150:151], v[86:87]
	s_waitcnt vmcnt(2) lgkmcnt(2)
	v_pk_fma_f32 v[170:171], v[60:61], v[156:157], v[92:93]
	v_pk_fma_f32 v[172:173], v[58:59], v[154:155], v[90:91]
	s_waitcnt vmcnt(1) lgkmcnt(1)
	v_pk_fma_f32 v[162:163], v[64:65], v[196:197], v[96:97]
	v_pk_fma_f32 v[168:169], v[62:63], v[194:195], v[94:95]
	s_waitcnt vmcnt(0) lgkmcnt(0)
	v_pk_fma_f32 v[166:167], v[68:69], v[200:201], v[100:101]
	v_pk_fma_f32 v[164:165], v[66:67], v[198:199], v[98:99]
	s_cbranch_scc0 .LBB0_336
.LBB0_337:
	s_bitcmp0_b32 s2, 0
	s_cbranch_scc1 .LBB0_339
	s_add_i32 s8, s7, s10
	s_ashr_i32 s9, s8, 31
	s_lshl_b64 s[8:9], s[8:9], 16
	v_lshl_add_u64 v[32:33], v[32:33], 0, s[8:9]
	s_movk_i32 s6, 0x1000
	global_load_dwordx4 v[36:39], v[32:33], off nt
	global_load_dwordx4 v[40:43], v[32:33], off offset:1024 nt
	global_load_dwordx4 v[44:47], v[32:33], off offset:2048 nt
	global_load_dwordx4 v[48:51], v[32:33], off offset:3072 nt
	v_add_co_u32_e32 v32, vcc, s6, v32
	s_lshl_b32 s6, s7, 9
	s_nop 0
	v_addc_co_u32_e32 v33, vcc, 0, v33, vcc
	global_load_dwordx4 v[52:55], v[32:33], off nt
	global_load_dwordx4 v[56:59], v[32:33], off offset:1024 nt
	global_load_dwordx4 v[60:63], v[32:33], off offset:2048 nt
	global_load_dwordx4 v[64:67], v[32:33], off offset:3072 nt
	s_add_i32 s6, s6, 0
	v_add_u32_e32 v32, s6, v35
	v_add_u32_e32 v32, 0x1a400, v32
	ds_read_b128 v[68:71], v32
	ds_read_b128 v[72:75], v32 offset:16
	ds_read_b128 v[76:79], v32 offset:128
	ds_read_b128 v[80:83], v32 offset:144
	ds_read_b128 v[84:87], v32 offset:256
	ds_read_b128 v[88:91], v32 offset:272
	ds_read_b128 v[92:95], v32 offset:384
	ds_read_b128 v[96:99], v32 offset:400
	s_waitcnt vmcnt(7) lgkmcnt(7)
	v_pk_fma_f32 v[190:191], v[190:191], v[70:71], v[38:39]
	v_pk_fma_f32 v[192:193], v[192:193], v[68:69], v[36:37]
	s_waitcnt vmcnt(6) lgkmcnt(6)
	v_pk_fma_f32 v[186:187], v[186:187], v[74:75], v[42:43]
	v_pk_fma_f32 v[188:189], v[188:189], v[72:73], v[40:41]
	s_waitcnt vmcnt(5) lgkmcnt(5)
	v_pk_fma_f32 v[182:183], v[182:183], v[78:79], v[46:47]
	v_pk_fma_f32 v[184:185], v[184:185], v[76:77], v[44:45]
	s_waitcnt vmcnt(4) lgkmcnt(4)
	v_pk_fma_f32 v[178:179], v[178:179], v[82:83], v[50:51]
	v_pk_fma_f32 v[180:181], v[180:181], v[80:81], v[48:49]
	s_waitcnt vmcnt(3) lgkmcnt(3)
	v_pk_fma_f32 v[174:175], v[174:175], v[86:87], v[54:55]
	v_pk_fma_f32 v[176:177], v[176:177], v[84:85], v[52:53]
	s_waitcnt vmcnt(2) lgkmcnt(2)
	v_pk_fma_f32 v[170:171], v[170:171], v[90:91], v[58:59]
	v_pk_fma_f32 v[172:173], v[172:173], v[88:89], v[56:57]
	s_waitcnt vmcnt(1) lgkmcnt(1)
	v_pk_fma_f32 v[162:163], v[162:163], v[94:95], v[62:63]
	v_pk_fma_f32 v[168:169], v[168:169], v[92:93], v[60:61]
	s_waitcnt vmcnt(0) lgkmcnt(0)
	v_pk_fma_f32 v[166:167], v[166:167], v[98:99], v[66:67]
	v_pk_fma_f32 v[164:165], v[164:165], v[96:97], v[64:65]

; #define LAS __attribute__((address_space(3)))
; __device__ __forceinline__ unsigned pk2(float lo, float hi) { return __builtin_bit_cast(unsigned, __builtin_convertvector((f32x2){lo, hi}, bf16x2_t)); }
; template <bool FULL> __device__ __forceinline__ void hg_load(const HgCtx& c, HgPref& r, int n) {
;     const size_t o = (size_t)n * 16 * 8192;
;     if (FULL) { r.q[0] = *(const u32x4*)(c.QI + o); r.q[1] = *(const u32x4*)(c.QI + o + 4096); }
;     r.k[0] = *(const u32x4*)(c.KI + o); r.k[1] = *(const u32x4*)(c.KI + o + 4096);
;     r.v[0] = *(const u32x4*)(c.VI + o); r.v[1] = *(const u32x4*)(c.VI + o + 4096); if (c.tid < 96) r.s = *(const u32x4*)(c.SCLG + (size_t)n * 16 * 384);
; }
; template <bool FULL, bool DEEP> __device__ __forceinline__ void hg_step(const HgCtx& c, int n, int i, int len, HgPref& P, HgPref& PN, f32x4 (&S)[8]) {
;     ...
;     if (FULL) {
; #pragma unroll
;         for (int it = 0; it < 4; ++it) gz4[it] = *(const u32x2*)(c.GZ + (size_t)n * 16 * 8192 + it * 2048);
; #pragma unroll
;         for (int it = 0; it < 4; ++it) o[it] = (f32x4){0.f, 0.f, 0.f, 0.f};
; #pragma unroll
;         for (int kk = 0; kk < 4; ++kk) {
;             const f32x4 e0 = *(const LAS f32x4*)(SCL + 32 * kk + 8 * fq), e1 = *(const LAS f32x4*)(SCL + 32 * kk + 8 * fq + 4);
;             const f32x4 s0 = S[2 * kk] * e0, s1 = S[2 * kk + 1] * e1;
;             const bf16x8 as = __builtin_bit_cast(bf16x8, (u32x4){pk2(s0[0], s0[1]), pk2(s0[2], s0[3]), pk2(s1[0], s1[1]), pk2(s1[2], s1[3])});
; #pragma unroll
;             for (int it = 0; it < 4; ++it) {
;                 const bf16x8 bq = *(const LAS bf16x8*)(QS + (16 * it + fr) * HP + 64 * kk + 16 * fq);
;                 o[it] = __builtin_amdgcn_mfma_f32_16x16x32_bf16(as, bq, o[it], 0, 0, 0);
;             }
;         }
.LBB0_344:
	v_lshl_add_u64 v[24:25], s[30:31], 0, v[200:201]
	v_add_co_u32_e32 v8, vcc, s3, v24
	s_waitcnt lgkmcnt(0)
	s_nop 0
	v_addc_co_u32_e32 v9, vcc, 0, v25, vcc
	v_add_co_u32_e32 v12, vcc, s63, v24
	s_barrier
	s_nop 0
	v_addc_co_u32_e32 v13, vcc, 0, v25, vcc
	v_add_co_u32_e32 v16, vcc, s64, v24
	s_nop 1
	v_addc_co_u32_e32 v17, vcc, 0, v25, vcc
	v_add_co_u32_e32 v20, vcc, 0x24742000, v24
	global_load_dwordx4 v[8:11], v[8:9], off nt
	s_nop 0
	global_load_dwordx4 v[12:15], v[12:13], off nt
	v_addc_co_u32_e32 v21, vcc, 0, v25, vcc
	v_add_co_u32_e32 v26, vcc, 0x28740000, v24
	global_load_dwordx4 v[16:19], v[16:17], off nt
	s_nop 0
	global_load_dwordx4 v[20:23], v[20:21], off nt
	v_addc_co_u32_e32 v27, vcc, 0, v25, vcc
	v_add_co_u32_e32 v28, vcc, 0x28742000, v24
	s_nop 1
	v_addc_co_u32_e32 v29, vcc, 0, v25, vcc
	global_load_dwordx4 v[24:27], v[26:27], off nt
	s_nop 0
	global_load_dwordx4 v[28:31], v[28:29], off nt
	s_and_saveexec_b64 s[22:23], s[0:1]
	s_cbranch_execz .LBB0_346
	v_lshl_add_u64 v[4:5], s[30:31], 0, v[198:199]
	global_load_dwordx4 v[4:7], v[4:5], off nt
.LBB0_346:
	s_or_b64 exec, exec, s[22:23]
	s_bitcmp1_b32 s65, 0
	s_cselect_b32 s22, 0xd200, 0
	s_add_i32 s22, s22, 0
	v_add_u32_e32 v76, s22, v238
	ds_read_b128 v[32:35], v76 offset:52224
	ds_read_b128 v[36:39], v76 offset:52240
	v_add_u32_e32 v159, s22, v214
	v_add_u32_e32 v77, v159, v213
	s_add_i32 s23, s22, s61
	s_waitcnt lgkmcnt(1)
	v_pk_mul_f32 v[34:35], v[190:191], v[34:35]
	v_pk_mul_f32 v[32:33], v[192:193], v[32:33]
	s_waitcnt lgkmcnt(0)
	v_pk_mul_f32 v[38:39], v[186:187], v[38:39]
	v_pk_mul_f32 v[36:37], v[188:189], v[36:37]
	v_cvt_pk_bf16_f32 v32, v32, v33
	v_cvt_pk_bf16_f32 v33, v34, v35
	v_cvt_pk_bf16_f32 v34, v36, v37
	v_cvt_pk_bf16_f32 v35, v38, v39
	ds_read_b128 v[36:39], v77
	ds_read_b128 v[40:43], v77 offset:64
	ds_read_b128 v[44:47], v77 offset:4352
	ds_read_b128 v[48:51], v77 offset:4416
	ds_read_b128 v[52:55], v77 offset:8704
	ds_read_b128 v[56:59], v77 offset:8768
	ds_read_b128 v[60:63], v77 offset:13056
	ds_read_b128 v[64:67], v76 offset:52352
	ds_read_b128 v[68:71], v76 offset:52368
	ds_read_b128 v[72:75], v77 offset:13120
	s_waitcnt lgkmcnt(9)
	v_mfma_f32_16x16x32_bf16 v[36:39], v[32:35], v[36:39], 0
	v_lshl_add_u64 v[84:85], s[30:31], 0, v[196:197]
	v_add_co_u32_e32 v86, vcc, 0x2c700000, v84
	s_waitcnt lgkmcnt(7)
	v_mfma_f32_16x16x32_bf16 v[44:47], v[32:35], v[44:47], 0
	v_addc_co_u32_e32 v87, vcc, 0, v85, vcc
	v_add_co_u32_e32 v88, vcc, 0x2c701000, v84
	s_waitcnt lgkmcnt(5)
	v_mfma_f32_16x16x32_bf16 v[52:55], v[32:35], v[52:55], 0
	v_addc_co_u32_e32 v89, vcc, 0, v85, vcc
	v_add_co_u32_e32 v90, vcc, 0x2c702000, v84
	s_waitcnt lgkmcnt(3)
	v_mfma_f32_16x16x32_bf16 v[32:35], v[32:35], v[60:63], 0
	s_waitcnt lgkmcnt(2)
	v_pk_mul_f32 v[62:63], v[182:183], v[66:67]
	v_pk_mul_f32 v[60:61], v[184:185], v[64:65]
	s_waitcnt lgkmcnt(1)
	v_pk_mul_f32 v[64:65], v[178:179], v[70:71]
	v_pk_mul_f32 v[66:67], v[180:181], v[68:69]
	v_cvt_pk_bf16_f32 v60, v60, v61
	v_cvt_pk_bf16_f32 v61, v62, v63
	v_cvt_pk_bf16_f32 v62, v66, v67
	v_cvt_pk_bf16_f32 v63, v64, v65
	v_addc_co_u32_e32 v91, vcc, 0, v85, vcc
	s_nop 0
	v_mfma_f32_16x16x32_bf16 v[36:39], v[60:63], v[40:43], v[36:39]
	v_lshl_add_u32 v152, v219, 2, s22
	v_add_u32_e32 v153, s22, v235
	v_cndmask_b32_e64 v154, 0, 1, s[46:47]
	v_mfma_f32_16x16x32_bf16 v[40:43], v[60:63], v[48:51], v[44:47]
	v_add_u32_e32 v242, v153, v214
	v_mov_b32_e32 v155, 0
	v_mov_b32_e32 v156, 0
	v_mfma_f32_16x16x32_bf16 v[44:47], v[60:63], v[56:59], v[52:55]
	ds_read_b128 v[48:51], v76 offset:52480
	s_nop 1
	ds_read_b128 v[52:55], v76 offset:52496
	v_mov_b32_e32 v157, 0
	s_waitcnt lgkmcnt(1)
	v_pk_mul_f32 v[50:51], v[174:175], v[50:51]
	v_pk_mul_f32 v[48:49], v[176:177], v[48:49]
	s_waitcnt lgkmcnt(0)
	v_pk_mul_f32 v[54:55], v[170:171], v[54:55]
	v_pk_mul_f32 v[52:53], v[172:173], v[52:53]
	v_cvt_pk_bf16_f32 v48, v48, v49
	v_cvt_pk_bf16_f32 v49, v50, v51
	v_cvt_pk_bf16_f32 v50, v52, v53
	v_cvt_pk_bf16_f32 v51, v54, v55
	ds_read_b128 v[52:55], v77 offset:128
	ds_read_b128 v[56:59], v77 offset:192
	v_mfma_f32_16x16x32_bf16 v[32:35], v[60:63], v[72:75], v[32:35]
	s_waitcnt lgkmcnt(1)
	v_mfma_f32_16x16x32_bf16 v[36:39], v[48:51], v[52:55], v[36:39]
	ds_read_b128 v[52:55], v77 offset:4480
	ds_read_b128 v[60:63], v77 offset:4544
	s_waitcnt lgkmcnt(1)
	v_mfma_f32_16x16x32_bf16 v[40:43], v[48:51], v[52:55], v[40:43]
	ds_read_b128 v[52:55], v77 offset:8832
	ds_read_b128 v[64:67], v77 offset:8896
	s_waitcnt lgkmcnt(1)
	v_mfma_f32_16x16x32_bf16 v[44:47], v[48:51], v[52:55], v[44:47]
	ds_read_b128 v[52:55], v77 offset:13184
	ds_read_b128 v[68:71], v76 offset:52608
	ds_read_b128 v[72:75], v76 offset:52624
	ds_read_b128 v[76:79], v77 offset:13248
	s_waitcnt lgkmcnt(3)
	v_mfma_f32_16x16x32_bf16 v[32:35], v[48:51], v[52:55], v[32:35]
	s_waitcnt lgkmcnt(2)
	v_pk_mul_f32 v[50:51], v[162:163], v[70:71]
	v_pk_mul_f32 v[48:49], v[168:169], v[68:69]
	s_waitcnt lgkmcnt(1)
	v_pk_mul_f32 v[52:53], v[166:167], v[74:75]
	v_pk_mul_f32 v[54:55], v[164:165], v[72:73]
	v_cvt_pk_bf16_f32 v48, v48, v49
	v_cvt_pk_bf16_f32 v49, v50, v51
	v_cvt_pk_bf16_f32 v50, v54, v55
	v_cvt_pk_bf16_f32 v51, v52, v53
	v_add3_u32 v72, s22, v240, v234
	s_waitcnt lgkmcnt(0)
; #define LAS __attribute__((address_space(3)))
; template <bool FULL, bool DEEP> __device__ __forceinline__ void hg_step(const HgCtx& c, int n, int i, int len, HgPref& P, HgPref& PN, f32x4 (&S)[8]) {
;     ...
;         for (int it = 0; it < 4; ++it) gz4[it] = *(const u32x2*)(c.GZ + (size_t)n * 16 * 8192 + it * 2048);
;     ...
;     bf16x8 vt[2];
; #pragma unroll
;     for (int ks = 0; ks < 2; ++ks) vt[ks] = tr_frag(VS + (32 * ks + 8 * fq + q4) * HP + (16 * w + 4 * p4) * 2);
; #pragma unroll
;     for (int dt = 0; dt < 8; ++dt) {
;         f32x4 tmp = (f32x4){0.f, 0.f, 0.f, 0.f};
; #pragma unroll
;         for (int ks = 0; ks < 2; ++ks) tmp = __builtin_amdgcn_mfma_f32_16x16x32_bf16(tr_frag(KS + (32 * ks + 8 * fq + q4) * HP + (32 * (dt >> 1) + 8 * p4 + 4 * (dt & 1)) * 2), vt[ks], tmp, 0, 0, 0);
;         const f32x4 el = *(const LAS f32x4*)(SCL + 128 + 32 * (dt >> 1) + 8 * fq + 4 * (dt & 1)), er = *(const LAS f32x4*)(SCL + 256 + 32 * (dt >> 1) + 8 * fq + 4 * (dt & 1));
;         S[dt] = el * S[dt] + er * tmp;
;     }
;     if (FULL) {
;         {
;             const int jt = w >> 1;
; #pragma unroll
;             for (int ii = 0; ii < 2; ++ii) {
;                 const int it = 2 * (w & 1) + ii;
;                 f32x4 sc = (f32x4){0.f, 0.f, 0.f, 0.f};
;                 if (jt <= it) {
; #pragma unroll
;                     for (int ks = 0; ks < 4; ++ks) {
;                         const bf16x8 ka = *(const LAS bf16x8*)(KS + (16 * jt + fr) * HP + 64 * ks + 16 * fq);
;                         const bf16x8 qb = *(const LAS bf16x8*)(QS + (16 * it + fr) * HP + 64 * ks + 16 * fq);
;                         sc = __builtin_amdgcn_mfma_f32_16x16x32_bf16(ka, qb, sc, 0, 0, 0);
;                     }
;                 }
	v_mfma_f32_16x16x32_bf16 v[132:135], v[48:51], v[76:79], v[32:35]
	s_nop 2
	v_add3_u32 v32, s23, v233, v234
	ds_read_b64_tr_b16 v[136:137], v32 offset:34816
	ds_read_b64_tr_b16 v[138:139], v32 offset:35904
	ds_read_b64_tr_b16 v[128:129], v32 offset:43520
	ds_read_b64_tr_b16 v[130:131], v32 offset:44608
	v_mfma_f32_16x16x32_bf16 v[144:147], v[48:51], v[56:59], v[36:39]
	v_cmp_ne_u32_e64 s[22:23], 1, v154
	v_mov_b32_e32 v154, 0
	v_mfma_f32_16x16x32_bf16 v[148:151], v[48:51], v[60:63], v[40:43]
	v_mfma_f32_16x16x32_bf16 v[140:143], v[48:51], v[64:67], v[44:47]
	ds_read_b64_tr_b16 v[34:35], v72 offset:18496
	ds_read_b64_tr_b16 v[32:33], v72 offset:17408
	ds_read_b64_tr_b16 v[36:37], v72 offset:26112
	ds_read_b64_tr_b16 v[38:39], v72 offset:27200
	ds_read_b64_tr_b16 v[40:41], v72 offset:17416
	ds_read_b64_tr_b16 v[48:49], v72 offset:17472
	ds_read_b64_tr_b16 v[52:53], v72 offset:17480
	ds_read_b64_tr_b16 v[42:43], v72 offset:18504
	ds_read_b64_tr_b16 v[50:51], v72 offset:18560
	ds_read_b64_tr_b16 v[54:55], v72 offset:18568
	ds_read_b64_tr_b16 v[56:57], v72 offset:26120
	ds_read_b64_tr_b16 v[60:61], v72 offset:26176
	ds_read_b64_tr_b16 v[64:65], v72 offset:26184
	ds_read_b64_tr_b16 v[58:59], v72 offset:27208
	ds_read_b64_tr_b16 v[62:63], v72 offset:27264
	ds_read_b64_tr_b16 v[66:67], v72 offset:27272
	s_waitcnt lgkmcnt(14)
	v_mfma_f32_16x16x32_bf16 v[32:35], v[32:35], v[136:139], 0
	s_waitcnt lgkmcnt(12)
	v_mfma_f32_16x16x32_bf16 v[44:47], v[36:39], v[128:131], v[32:35]
	s_waitcnt lgkmcnt(8)
	v_mfma_f32_16x16x32_bf16 v[32:35], v[40:43], v[136:139], 0
	s_waitcnt lgkmcnt(2)
	v_mfma_f32_16x16x32_bf16 v[40:43], v[56:59], v[128:131], v[32:35]
	v_mfma_f32_16x16x32_bf16 v[32:35], v[48:51], v[136:139], 0
	s_waitcnt lgkmcnt(1)
	v_mfma_f32_16x16x32_bf16 v[36:39], v[60:63], v[128:131], v[32:35]
	v_mfma_f32_16x16x32_bf16 v[32:35], v[52:55], v[136:139], 0
	ds_read_b64_tr_b16 v[48:49], v72 offset:17536
	ds_read_b64_tr_b16 v[50:51], v72 offset:18624
	ds_read_b64_tr_b16 v[52:53], v72 offset:26240
	ds_read_b64_tr_b16 v[54:55], v72 offset:27328
	ds_read_b64_tr_b16 v[56:57], v72 offset:17544
	ds_read_b64_tr_b16 v[60:61], v72 offset:17600
	ds_read_b64_tr_b16 v[68:69], v72 offset:17608
	ds_read_b64_tr_b16 v[58:59], v72 offset:18632
	ds_read_b64_tr_b16 v[62:63], v72 offset:18688
	ds_read_b64_tr_b16 v[70:71], v72 offset:18696
	s_waitcnt lgkmcnt(8)
	v_mfma_f32_16x16x32_bf16 v[48:51], v[48:51], v[136:139], 0
	v_mfma_f32_16x16x32_bf16 v[32:35], v[64:67], v[128:131], v[32:35]
	ds_read_b64_tr_b16 v[64:65], v72 offset:26248
	ds_read_b64_tr_b16 v[76:77], v72 offset:26304
	ds_read_b64_tr_b16 v[80:81], v72 offset:26312
	ds_read_b64_tr_b16 v[66:67], v72 offset:27336
	ds_read_b64_tr_b16 v[78:79], v72 offset:27392
	ds_read_b64_tr_b16 v[82:83], v72 offset:27400
	s_waitcnt lgkmcnt(12)
	v_mfma_f32_16x16x32_bf16 v[72:75], v[52:55], v[128:131], v[48:51]
	v_add_co_u32_e32 v52, vcc, 0x2c703000, v84
	s_nop 1
	v_addc_co_u32_e32 v53, vcc, 0, v85, vcc
	global_load_dwordx2 v[208:209], v[86:87], off nt
	global_load_dwordx2 v[206:207], v[88:89], off nt
	global_load_dwordx2 v[204:205], v[90:91], off nt
	global_load_dwordx2 v[202:203], v[52:53], off nt
	s_waitcnt lgkmcnt(8)
	v_mfma_f32_16x16x32_bf16 v[48:51], v[56:59], v[136:139], 0
	ds_read_b128 v[120:123], v152 offset:52736
	ds_read_b128 v[112:115], v152 offset:52752
	ds_read_b128 v[124:127], v152 offset:53248
	ds_read_b128 v[116:119], v152 offset:53264
	ds_read_b128 v[104:107], v152 offset:52864
	ds_read_b128 v[96:99], v152 offset:52880
	ds_read_b128 v[108:111], v152 offset:53376
	ds_read_b128 v[100:103], v152 offset:53392
	s_andn2_b64 vcc, exec, s[46:47]
	s_waitcnt lgkmcnt(10)
	v_mfma_f32_16x16x32_bf16 v[64:67], v[64:67], v[128:131], v[48:51]
	v_mfma_f32_16x16x32_bf16 v[48:51], v[60:63], v[136:139], 0
	s_waitcnt lgkmcnt(9)
	v_mfma_f32_16x16x32_bf16 v[56:59], v[76:79], v[128:131], v[48:51]
	ds_read_b128 v[88:91], v152 offset:52992
	ds_read_b128 v[76:79], v152 offset:53008
	ds_read_b128 v[92:95], v152 offset:53504
	ds_read_b128 v[84:87], v152 offset:53520
	v_mfma_f32_16x16x32_bf16 v[48:51], v[68:71], v[136:139], 0
	s_waitcnt lgkmcnt(12)
	v_mfma_f32_16x16x32_bf16 v[52:55], v[80:83], v[128:131], v[48:51]
	ds_read_b128 v[68:71], v152 offset:53120
	s_nop 4
	ds_read_b128 v[48:51], v152 offset:53136
	ds_read_b128 v[80:83], v152 offset:53632
	ds_read_b128 v[60:63], v152 offset:53648
	v_mov_b32_e32 v152, 0
	s_cbranch_vccnz .LBB0_348
	v_add_u32_e32 v153, v159, v236
	ds_read_b128 v[154:157], v242 offset:17408
	ds_read_b128 v[244:247], v153
	s_waitcnt lgkmcnt(0)
	v_mfma_f32_16x16x32_bf16 v[154:157], v[154:157], v[244:247], 0
	ds_read_b128 v[244:247], v242 offset:17472
	ds_read_b128 v[248:251], v153 offset:64
	s_waitcnt lgkmcnt(0)
	v_mfma_f32_16x16x32_bf16 v[154:157], v[244:247], v[248:251], v[154:157]
	ds_read_b128 v[244:247], v242 offset:17536
	ds_read_b128 v[248:251], v153 offset:128
	s_waitcnt lgkmcnt(0)
	v_mfma_f32_16x16x32_bf16 v[154:157], v[244:247], v[248:251], v[154:157]
	ds_read_b128 v[244:247], v242 offset:17600
	ds_read_b128 v[248:251], v153 offset:192
	s_waitcnt lgkmcnt(0)
	v_mfma_f32_16x16x32_bf16 v[154:157], v[244:247], v[248:251], v[154:157]

; #define LAS __attribute__((address_space(3)))
; __device__ __forceinline__ unsigned pk2(float lo, float hi) { return __builtin_bit_cast(unsigned, __builtin_convertvector((f32x2){lo, hi}, bf16x2_t)); }
; template <bool FULL, bool DEEP> __device__ __forceinline__ void hg_step(const HgCtx& c, int n, int i, int len, HgPref& P, HgPref& PN, f32x4 (&S)[8]) {
;     ...
;     if (FULL) {
; #pragma unroll
;         for (int it = 0; it < 4; ++it) gz4[it] = *(const u32x2*)(c.GZ + (size_t)n * 16 * 8192 + it * 2048);
; #pragma unroll
;         for (int it = 0; it < 4; ++it) o[it] = (f32x4){0.f, 0.f, 0.f, 0.f};
; #pragma unroll
;         for (int kk = 0; kk < 4; ++kk) {
;             const f32x4 e0 = *(const LAS f32x4*)(SCL + 32 * kk + 8 * fq), e1 = *(const LAS f32x4*)(SCL + 32 * kk + 8 * fq + 4);
;             const f32x4 s0 = S[2 * kk] * e0, s1 = S[2 * kk + 1] * e1;
;             const bf16x8 as = __builtin_bit_cast(bf16x8, (u32x4){pk2(s0[0], s0[1]), pk2(s0[2], s0[3]), pk2(s1[0], s1[1]), pk2(s1[2], s1[3])});
; #pragma unroll
;             for (int it = 0; it < 4; ++it) {
;                 const bf16x8 bq = *(const LAS bf16x8*)(QS + (16 * it + fr) * HP + 64 * kk + 16 * fq);
;                 o[it] = __builtin_amdgcn_mfma_f32_16x16x32_bf16(as, bq, o[it], 0, 0, 0);
;             }
;         }
;     }
;     bf16x8 vt[2];
; #pragma unroll
;     for (int ks = 0; ks < 2; ++ks) vt[ks] = tr_frag(VS + (32 * ks + 8 * fq + q4) * HP + (16 * w + 4 * p4) * 2);
; #pragma unroll
;     for (int dt = 0; dt < 8; ++dt) {
;         f32x4 tmp = (f32x4){0.f, 0.f, 0.f, 0.f};
; #pragma unroll
;         for (int ks = 0; ks < 2; ++ks) tmp = __builtin_amdgcn_mfma_f32_16x16x32_bf16(tr_frag(KS + (32 * ks + 8 * fq + q4) * HP + (32 * (dt >> 1) + 8 * p4 + 4 * (dt & 1)) * 2), vt[ks], tmp, 0, 0, 0);
;     ...
;                 if (jt <= it) {
; #pragma unroll
;                     for (int ks = 0; ks < 4; ++ks) {
;                         const bf16x8 ka = *(const LAS bf16x8*)(KS + (16 * jt + fr) * HP + 64 * ks + 16 * fq);
;                         const bf16x8 qb = *(const LAS bf16x8*)(QS + (16 * it + fr) * HP + 64 * ks + 16 * fq);
;                         sc = __builtin_amdgcn_mfma_f32_16x16x32_bf16(ka, qb, sc, 0, 0, 0);
;                     }
;                 }
.LBB0_360:
	v_add_u32_e32 v4, 0, v238
	v_add_u32_e32 v41, 0x19e00, v4
	s_waitcnt lgkmcnt(0)
	s_barrier
	ds_read_b128 v[4:7], v41
	ds_read_b128 v[8:11], v41 offset:16
	v_add_u32_e32 v40, 0, v214
	v_add_u32_e32 v46, v40, v213
	v_add_u32_e32 v52, 0x1100, v46
	s_waitcnt lgkmcnt(1)
	v_pk_mul_f32 v[6:7], v[190:191], v[6:7]
	v_pk_mul_f32 v[4:5], v[192:193], v[4:5]
	s_waitcnt lgkmcnt(0)
	v_pk_mul_f32 v[10:11], v[186:187], v[10:11]
	v_pk_mul_f32 v[8:9], v[188:189], v[8:9]
	v_cvt_pk_bf16_f32 v4, v4, v5
	v_cvt_pk_bf16_f32 v5, v6, v7
	v_cvt_pk_bf16_f32 v6, v8, v9
	v_cvt_pk_bf16_f32 v7, v10, v11
	ds_read_b128 v[8:11], v46 offset:53760
	ds_read_b128 v[12:15], v46 offset:53824
	ds_read_b128 v[16:19], v46 offset:58112
	ds_read_b128 v[20:23], v46 offset:62464
	ds_read_b128 v[24:27], v46 offset:58176
	ds_read_b128 v[28:31], v41 offset:128
	ds_read_b128 v[32:35], v46 offset:62528
	ds_read_b128 v[36:39], v41 offset:144
	ds_read_b128 v[42:45], v52 offset:62464
	s_waitcnt lgkmcnt(8)
	v_mfma_f32_16x16x32_bf16 v[8:11], v[4:7], v[8:11], 0
	s_waitcnt lgkmcnt(3)
	v_pk_mul_f32 v[30:31], v[182:183], v[30:31]
	v_pk_mul_f32 v[28:29], v[184:185], v[28:29]
	s_waitcnt lgkmcnt(1)
	v_pk_mul_f32 v[38:39], v[178:179], v[38:39]
	v_pk_mul_f32 v[36:37], v[180:181], v[36:37]
	v_cvt_pk_bf16_f32 v28, v28, v29
	v_cvt_pk_bf16_f32 v29, v30, v31
	v_cvt_pk_bf16_f32 v30, v36, v37
	v_cvt_pk_bf16_f32 v31, v38, v39
	v_mfma_f32_16x16x32_bf16 v[16:19], v[4:7], v[16:19], 0
	ds_read_b128 v[36:39], v52 offset:62528
	s_lshl_b64 s[0:1], s[40:41], 1
	s_add_u32 s0, s30, s0
	v_mfma_f32_16x16x32_bf16 v[8:11], v[28:31], v[12:15], v[8:11]
	s_addc_u32 s1, s31, s1
	v_mov_b32_e32 v195, 0
	s_mov_b32 s41, 0
	v_mfma_f32_16x16x32_bf16 v[12:15], v[28:31], v[24:27], v[16:19]
	ds_read_b128 v[24:27], v41 offset:272
	s_lshl_b32 s40, s35, 1
	s_or_b32 s3, s34, 15
	ds_read_b128 v[16:19], v41 offset:256
	v_mfma_f32_16x16x32_bf16 v[20:23], v[4:7], v[20:23], 0
	s_waitcnt lgkmcnt(1)
	v_pk_mul_f32 v[26:27], v[170:171], v[26:27]
	v_pk_mul_f32 v[24:25], v[172:173], v[24:25]
	s_waitcnt lgkmcnt(0)
	v_pk_mul_f32 v[18:19], v[174:175], v[18:19]
	v_pk_mul_f32 v[16:17], v[176:177], v[16:17]
	v_mfma_f32_16x16x32_bf16 v[4:7], v[4:7], v[42:45], 0
	v_cvt_pk_bf16_f32 v16, v16, v17
	v_cvt_pk_bf16_f32 v17, v18, v19
	v_cvt_pk_bf16_f32 v18, v24, v25
	v_cvt_pk_bf16_f32 v19, v26, v27
	ds_read_b128 v[24:27], v46 offset:53888
	v_mfma_f32_16x16x32_bf16 v[20:23], v[28:31], v[32:35], v[20:23]
	v_lshl_add_u64 v[42:43], s[0:1], 0, v[194:195]
	v_lshl_add_u64 v[42:43], v[42:43], 0, s[40:41]
	v_lshlrev_b32_e32 v194, 1, v215
	v_mfma_f32_16x16x32_bf16 v[4:7], v[28:31], v[36:39], v[4:7]
	ds_read_b128 v[28:31], v46 offset:58240
	ds_read_b128 v[32:35], v46 offset:53952
	v_lshl_add_u64 v[50:51], v[42:43], 0, v[194:195]
	s_lshl_b32 s40, s3, 18
	s_waitcnt lgkmcnt(2)
	v_mfma_f32_16x16x32_bf16 v[8:11], v[16:19], v[24:27], v[8:11]
	ds_read_b128 v[24:27], v46 offset:62592
	ds_read_b128 v[36:39], v46 offset:58304
	s_mov_b32 s0, 0x2c701000
	s_waitcnt lgkmcnt(3)
	v_mfma_f32_16x16x32_bf16 v[12:15], v[16:19], v[28:31], v[12:15]
	ds_read_b128 v[28:31], v41 offset:384
	ds_read_b128 v[42:45], v41 offset:400
	ds_read_b128 v[46:49], v46 offset:62656
	s_waitcnt lgkmcnt(2)
	v_pk_mul_f32 v[30:31], v[162:163], v[30:31]
	v_mfma_f32_16x16x32_bf16 v[20:23], v[16:19], v[24:27], v[20:23]
	ds_read_b128 v[24:27], v52 offset:62592
	v_pk_mul_f32 v[28:29], v[168:169], v[28:29]
	s_waitcnt lgkmcnt(2)
	v_pk_mul_f32 v[44:45], v[166:167], v[44:45]
	v_pk_mul_f32 v[42:43], v[164:165], v[42:43]
	v_cvt_pk_bf16_f32 v28, v28, v29
	v_cvt_pk_bf16_f32 v29, v30, v31
	v_cvt_pk_bf16_f32 v30, v42, v43
	v_cvt_pk_bf16_f32 v31, v44, v45
	ds_read_b128 v[42:45], v52 offset:62656
	s_waitcnt lgkmcnt(1)
	v_mfma_f32_16x16x32_bf16 v[4:7], v[16:19], v[24:27], v[4:7]
	v_lshl_add_u64 v[16:17], v[50:51], 0, s[40:41]
	v_add_co_u32_e32 v18, vcc, s0, v16
	s_mov_b32 s0, 0x2c703000
	s_nop 0
	v_addc_co_u32_e32 v19, vcc, 0, v17, vcc
	v_add_co_u32_e32 v16, vcc, s0, v16
	v_mfma_f32_16x16x32_bf16 v[8:11], v[28:31], v[32:35], v[8:11]
	s_nop 0
	v_addc_co_u32_e32 v17, vcc, 0, v17, vcc
	s_add_i32 s0, s61, 0
	v_mfma_f32_16x16x32_bf16 v[12:15], v[28:31], v[36:39], v[12:15]
	global_load_dwordx2 v[38:39], v[18:19], off offset:-4096 nt
	global_load_dwordx2 v[36:37], v[18:19], off nt
	global_load_dwordx2 v[34:35], v[16:17], off offset:-4096 nt
	global_load_dwordx2 v[32:33], v[16:17], off nt
	s_add_i32 s0, s0, 0x15a00
	s_and_b64 vcc, exec, s[22:23]
	s_waitcnt lgkmcnt(0)
	v_mfma_f32_16x16x32_bf16 v[24:27], v[28:31], v[42:45], v[4:7]
	v_mov_b32_e32 v17, 0
	v_mov_b32_e32 v18, 0
	v_mov_b32_e32 v19, 0
	v_add3_u32 v6, s0, v233, v234
	v_mfma_f32_16x16x32_bf16 v[20:23], v[28:31], v[46:49], v[20:23]
	ds_read_b64_tr_b16 v[28:29], v6
	ds_read_b64_tr_b16 v[30:31], v6 offset:1088
	ds_read_b64_tr_b16 v[4:5], v6 offset:8704
	ds_read_b64_tr_b16 v[6:7], v6 offset:9792
	s_add_i32 s0, 0, 0x11600
	v_add_u32_e32 v16, s0, v235
	v_add_u32_e32 v41, v16, v214
	v_mov_b32_e32 v16, 0
	s_cbranch_vccnz .LBB0_362
	ds_read_b128 v[16:19], v41
	v_add_u32_e32 v58, v40, v236
	ds_read_b128 v[42:45], v41 offset:64
	ds_read_b128 v[46:49], v58 offset:53760
	ds_read_b128 v[50:53], v58 offset:53824
	s_waitcnt lgkmcnt(1)
	v_mfma_f32_16x16x32_bf16 v[16:19], v[16:19], v[46:49], 0
	ds_read_b128 v[46:49], v41 offset:128
	ds_read_b128 v[54:57], v41 offset:192
	s_waitcnt lgkmcnt(2)
	v_mfma_f32_16x16x32_bf16 v[16:19], v[42:45], v[50:53], v[16:19]
	ds_read_b128 v[42:45], v58 offset:53888
	ds_read_b128 v[50:53], v58 offset:53952
	s_waitcnt lgkmcnt(1)
	v_mfma_f32_16x16x32_bf16 v[16:19], v[46:49], v[42:45], v[16:19]
	s_waitcnt lgkmcnt(0)
	v_mfma_f32_16x16x32_bf16 v[16:19], v[54:57], v[50:53], v[16:19]

; __device__ __forceinline__ unsigned pk2(float lo, float hi) { return __builtin_bit_cast(unsigned, __builtin_convertvector((f32x2){lo, hi}, bf16x2_t)); }
; __device__ __forceinline__ void gm_load(const Args& a, int g, int blk, GmIn& r) {
;     const int tid = threadIdx.x, l = tid & 63, w = __builtin_amdgcn_readfirstlane(tid >> 6), fr = l & 15, fq = l >> 4;
;     const size_t t0 = (size_t)blk * 128;
;     const bf16_t* GV = (const bf16_t*)(a.ws + WS_GV); const bf16_t* GUZ = (const bf16_t*)(a.ws + WS_GUZ);
;     const float* lns = (const float*)(a.ws + WS_LNS);
; #pragma unroll
;     for (int i = 0; i < 4; ++i) { const int c16 = tid + 512 * i; r.gv[i] = *(const u32x4*)(GV + (t0 + (c16 >> 4)) * BW + g * 128 + (c16 & 15) * 8); }
; template <bool FULL, bool DEEP> __device__ __forceinline__ void hg_step(const HgCtx& c, int n, int i, int len, HgPref& P, HgPref& PN, f32x4 (&S)[8]) {
;     ...
; #pragma unroll
;         for (int it = 0; it < 4; ++it) {
;             float tot = NS[(2 * fq) * 64 + 16 * it + fr] + NS[(2 * fq + 1) * 64 + 16 * it + fr];
;             tot += __shfl_xor(tot, 16); tot += __shfl_xor(tot, 32);
;             const float rstd = __builtin_amdgcn_rsqf(tot * (1.0f / 128.0f) + EPS);
;             const u32x2 g4 = gz4[it];
;             *(u32x2*)((char*)c.H + tiled_off(c.hrow + n * 64 + 16 * it, c.hcol)) = (u32x2){pk2(o[it][0] * rstd * c.nw4[0] * bflo(g4.x), o[it][1] * rstd * c.nw4[1] * bfhi(g4.x)),
;                                                                       pk2(o[it][2] * rstd * c.nw4[2] * bflo(g4.y), o[it][3] * rstd * c.nw4[3] * bfhi(g4.y))};
;         }
.LBB0_372:
	s_or_b64 exec, exec, s[0:1]
	s_waitcnt lgkmcnt(0)
	s_barrier
	ds_read2_b32 v[20:21], v228 offset1:16
	ds_read2_b32 v[22:23], v228 offset0:64 offset1:80
	v_mov_b32_e32 v28, 0x358637bd
	s_waitcnt vmcnt(3)
	v_lshlrev_b32_e32 v24, 16, v38
	v_and_b32_e32 v25, 0xffff0000, v38
	v_lshlrev_b32_e32 v26, 16, v39
	s_waitcnt lgkmcnt(0)
	v_add_f32_e32 v20, v20, v22
	ds_bpermute_b32 v22, v227, v20
	v_and_b32_e32 v27, 0xffff0000, v39
	s_or_b32 s4, s3, s60
	s_lshl_b32 s0, s4, 6
	s_ashr_i32 s0, s0, 1
	s_waitcnt lgkmcnt(0)
	v_add_f32_e32 v20, v20, v22
	ds_bpermute_b32 v22, v226, v20
	s_andn2_b32 s0, s0, 63
	s_add_i32 s0, s0, s59
	s_ashr_i32 s1, s0, 31
	v_lshlrev_b32_e32 v96, 6, v218
	s_waitcnt lgkmcnt(0)
	v_add_f32_e32 v20, v20, v22
	v_fmamk_f32 v20, v20, 0x3c000000, v28
	v_rsq_f32_e32 v20, v20
	s_lshl_b64 s[0:1], s[0:1], 14
	s_lshl_b32 s3, s58, 10
	s_add_u32 s0, s26, s0
	v_pk_mul_f32 v[16:17], v[16:17], v[20:21] op_sel_hi:[1,0]
	v_pk_mul_f32 v[18:19], v[18:19], v[20:21] op_sel_hi:[1,0]
	v_pk_mul_f32 v[16:17], v[0:1], v[16:17]
	v_pk_mul_f32 v[18:19], v[2:3], v[18:19]
	v_pk_mul_f32 v[16:17], v[16:17], v[24:25]
	v_pk_mul_f32 v[18:19], v[18:19], v[26:27]
	v_cvt_pk_bf16_f32 v16, v16, v17
	v_cvt_pk_bf16_f32 v17, v18, v19
	v_add_f32_e32 v18, v21, v23
	ds_bpermute_b32 v19, v227, v18
	v_or_b32_e32 v24, v96, v229
	v_bitop3_b32 v20, v24, s3, v132 bitop3:0xde
	v_or_b32_e32 v20, 0x2000, v20
	s_addc_u32 s1, s27, s1
	s_waitcnt lgkmcnt(0)
	v_add_f32_e32 v18, v18, v19
	ds_bpermute_b32 v19, v226, v18
	global_store_dwordx2 v20, v[16:17], s[0:1]
	s_waitcnt vmcnt(3)
	v_lshlrev_b32_e32 v16, 16, v36
	v_and_b32_e32 v17, 0xffff0000, v36
	v_lshlrev_b32_e32 v22, 16, v37
	s_waitcnt lgkmcnt(0)
	v_add_f32_e32 v18, v18, v19
	v_fmamk_f32 v18, v18, 0x3c000000, v28
	v_rsq_f32_e32 v18, v18
	v_and_b32_e32 v23, 0xffff0000, v37
	s_lshl_b32 s4, s4, 3
	s_or_b32 s5, s4, 2
	v_pk_mul_f32 v[12:13], v[12:13], v[18:19] op_sel_hi:[1,0]
	v_pk_mul_f32 v[14:15], v[14:15], v[18:19] op_sel_hi:[1,0]
	v_pk_mul_f32 v[12:13], v[0:1], v[12:13]
	v_pk_mul_f32 v[14:15], v[2:3], v[14:15]
	v_pk_mul_f32 v[12:13], v[12:13], v[16:17]
	ds_read2_b32 v[16:17], v228 offset0:32 offset1:48
	ds_read2_b32 v[20:21], v228 offset0:96 offset1:112
	v_pk_mul_f32 v[14:15], v[14:15], v[22:23]
	v_cvt_pk_bf16_f32 v12, v12, v13
	v_cvt_pk_bf16_f32 v13, v14, v15
	s_and_b32 s5, s5, 10
	s_waitcnt lgkmcnt(0)
	v_add_f32_e32 v16, v16, v20
	ds_bpermute_b32 v18, v227, v16
	s_or_b32 s5, s5, s58
	s_lshl_b32 s5, s5, 10
	s_and_b32 s7, s2, 15
	s_lshl_b32 s9, s7, 7
	s_waitcnt lgkmcnt(0)
	v_add_f32_e32 v14, v16, v18
	ds_bpermute_b32 v15, v226, v14
	v_bitop3_b32 v16, v24, s5, v132 bitop3:0xde
	global_store_dwordx2 v16, v[12:13], s[0:1]
	s_waitcnt vmcnt(3)
	v_lshlrev_b32_e32 v12, 16, v34
	v_and_b32_e32 v13, 0xffff0000, v34
	s_waitcnt lgkmcnt(0)
	v_add_f32_e32 v14, v14, v15
	v_fmamk_f32 v14, v14, 0x3c000000, v28
	v_rsq_f32_e32 v14, v14
	s_or_b32 s5, s4, 4
	s_and_b32 s5, s5, 12
	s_or_b32 s5, s5, s58
	v_pk_mul_f32 v[8:9], v[8:9], v[14:15] op_sel_hi:[1,0]
	v_pk_mul_f32 v[10:11], v[10:11], v[14:15] op_sel_hi:[1,0]
	v_add_f32_e32 v14, v17, v21
	ds_bpermute_b32 v15, v227, v14
	v_pk_mul_f32 v[8:9], v[0:1], v[8:9]
	v_pk_mul_f32 v[10:11], v[2:3], v[10:11]
	v_pk_mul_f32 v[8:9], v[8:9], v[12:13]
	v_lshlrev_b32_e32 v12, 16, v35
	v_and_b32_e32 v13, 0xffff0000, v35
	v_pk_mul_f32 v[10:11], v[10:11], v[12:13]
	v_cvt_pk_bf16_f32 v8, v8, v9
	v_cvt_pk_bf16_f32 v9, v10, v11
	s_waitcnt lgkmcnt(0)
	v_add_f32_e32 v10, v14, v15
	ds_bpermute_b32 v11, v226, v10
	s_lshl_b32 s5, s5, 10
	s_or_b32 s4, s4, 6
	v_bitop3_b32 v12, v24, s5, v132 bitop3:0xde
	s_and_b32 s4, s4, 14
	s_waitcnt lgkmcnt(0)
	v_add_f32_e32 v10, v10, v11
	v_fmac_f32_e32 v28, 0x3c000000, v10
	v_rsq_f32_e32 v10, v28
	global_store_dwordx2 v12, v[8:9], s[0:1]
	s_waitcnt vmcnt(3)
	v_lshlrev_b32_e32 v8, 16, v32
	v_and_b32_e32 v9, 0xffff0000, v32
	v_pk_mul_f32 v[4:5], v[4:5], v[10:11] op_sel_hi:[1,0]
	v_pk_mul_f32 v[6:7], v[6:7], v[10:11] op_sel_hi:[1,0]
	v_pk_mul_f32 v[0:1], v[0:1], v[4:5]
	v_lshlrev_b32_e32 v4, 16, v33
	v_and_b32_e32 v5, 0xffff0000, v33
	v_pk_mul_f32 v[2:3], v[2:3], v[6:7]
	s_or_b32 s4, s4, s58
	v_pk_mul_f32 v[0:1], v[0:1], v[8:9]
	v_pk_mul_f32 v[2:3], v[2:3], v[4:5]
	s_lshl_b32 s4, s4, 10
	v_cvt_pk_bf16_f32 v0, v0, v1
	v_cvt_pk_bf16_f32 v1, v2, v3
	v_bitop3_b32 v2, v24, s4, v132 bitop3:0xde
	s_ashr_i32 s4, s2, 4
	s_ashr_i32 s5, s4, 31
	global_store_dwordx2 v2, v[0:1], s[0:1]
	s_lshl_b64 s[0:1], s[4:5], 7
	s_lshl_b32 s6, s7, 8
	s_add_u32 s10, s30, s6
	v_and_b32_e32 v0, 0x78, v212
	s_addc_u32 s11, s31, 0
	v_lshlrev_b32_e32 v48, 1, v0
	v_mov_b32_e32 v49, 0
	v_lshl_add_u64 v[0:1], s[10:11], 0, v[48:49]
	s_mov_b64 s[10:11], 0x1c700000
	v_or_b32_e32 v46, s0, v216
	v_mov_b32_e32 v47, s1
	v_add_u32_e32 v20, 0x200, v210
	v_lshl_add_u64 v[8:9], v[0:1], 0, s[10:11]
	v_lshlrev_b64 v[0:1], 12, v[46:47]
	v_lshrrev_b32_e32 v97, 4, v20
	v_lshl_add_u64 v[10:11], v[8:9], 0, v[0:1]
	v_or_b32_e32 v0, s0, v97
	v_mov_b32_e32 v1, s1
	v_lshlrev_b64 v[0:1], 12, v[0:1]
	v_or_b32_e32 v46, 64, v46
	v_add_u32_e32 v26, 0x600, v210
	s_barrier
; #define LAS __attribute__((address_space(3)))
; __device__ __forceinline__ void gm_load(const Args& a, int g, int blk, GmIn& r) {
;     const int tid = threadIdx.x, l = tid & 63, w = __builtin_amdgcn_readfirstlane(tid >> 6), fr = l & 15, fq = l >> 4;
;     const size_t t0 = (size_t)blk * 128;
;     const bf16_t* GV = (const bf16_t*)(a.ws + WS_GV); const bf16_t* GUZ = (const bf16_t*)(a.ws + WS_GUZ);
;     const float* lns = (const float*)(a.ws + WS_LNS);
; #pragma unroll
;     for (int i = 0; i < 4; ++i) { const int c16 = tid + 512 * i; r.gv[i] = *(const u32x4*)(GV + (t0 + (c16 >> 4)) * BW + g * 128 + (c16 & 15) * 8); }
;     { const f32x4* p = (const f32x4*)(lns + ((t0 + (tid >> 2)) * 32 + (tid & 3) * 8) * 2);
; #pragma unroll
;       for (int k = 0; k < 4; ++k) r.st[k] = p[k]; }
;     const int cc = g * 128 + 16 * w + 4 * fq;
; #pragma unroll
;     for (int it = 0; it < 8; ++it) r.guz[it] = *(const u32x2*)(GUZ + (t0 + 16 * it + fr) * BW + cc);
; __device__ __forceinline__ void gmlp_phase(const Args& a, LAS unsigned char* lds, int bid) {
;     ...
;         const bf16_t* WM = (const bf16_t*)(a.ws + WS_WM) + (size_t)g * 128 * 128;
; #pragma unroll
;         for (int i = 0; i < 4; ++i) { const int c16 = tid + 512 * i; *(LAS u32x4*)(lds + GL_WM + (c16 >> 4) * 272 + (c16 & 15) * 16) = *(const u32x4*)(WM + (size_t)c16 * 8); }
;     }
;     const int c = g * 128 + 16 * w + fr, cc = g * 128 + 16 * w + 4 * fq;
;     const float lnw = a.ln_w[c], lnb = a.ln_b[c];
;     float bias[8];
; #pragma unroll
;     for (int it = 0; it < 8; ++it) bias[it] = a.b_s[g * 128 + 16 * it + fr];
	v_lshl_add_u64 v[12:13], v[8:9], 0, v[0:1]
	global_load_dwordx4 v[0:3], v[10:11], off nt
	global_load_dwordx4 v[4:7], v[12:13], off nt
	v_lshlrev_b64 v[10:11], 12, v[46:47]
	v_lshrrev_b32_e32 v48, 4, v26
	v_lshl_add_u64 v[16:17], v[8:9], 0, v[10:11]
	v_lshl_add_u64 v[10:11], s[0:1], 0, v[48:49]
	v_lshlrev_b64 v[10:11], 12, v[10:11]
	v_lshrrev_b32_e32 v32, 2, v210
	v_mov_b32_e32 v33, v49
	v_lshl_add_u64 v[18:19], v[8:9], 0, v[10:11]
	global_load_dwordx4 v[8:11], v[16:17], off nt
	global_load_dwordx4 v[12:15], v[18:19], off nt
	v_lshl_add_u64 v[16:17], s[0:1], 0, v[32:33]
	v_and_b32_e32 v18, 48, v160
	v_lshlrev_b64 v[16:17], 8, v[16:17]
	v_lshl_add_u64 v[16:17], s[30:31], 0, v[16:17]
	v_lshlrev_b32_e32 v18, 2, v18
	v_mov_b32_e32 v19, v49
	v_readfirstlane_b32 s8, v210
	v_lshl_add_u64 v[16:17], v[16:17], 0, v[18:19]
	s_mov_b64 s[10:11], 0x48b00000
	v_lshl_add_u64 v[50:51], v[16:17], 0, s[10:11]
	s_lshr_b32 s10, s8, 2
	s_and_b32 s11, s10, 0x3ffffff0
	s_add_i32 s10, s11, s9
	s_lshl_b32 s7, s7, 15
	s_add_u32 s7, s30, s7
	s_mov_b32 s1, 0x48b00000
	s_addc_u32 s13, s31, 0
	s_add_u32 s12, s7, 0x48900000
	v_add_co_u32_e32 v24, vcc, s1, v16
	v_or_b32_e32 v33, 0x400, v210
	s_addc_u32 s13, s13, 0
	v_lshlrev_b32_e32 v18, 1, v212
	v_addc_co_u32_e32 v25, vcc, 0, v17, vcc
	v_lshlrev_b32_e32 v16, 4, v20
	v_lshlrev_b32_e32 v27, 4, v33
	v_lshlrev_b32_e32 v46, 4, v26
	v_and_b32_e32 v55, 12, v32
	global_load_dwordx4 v[34:37], v18, s[12:13] nt
	global_load_dwordx4 v[38:41], v16, s[12:13] nt
	global_load_dwordx4 v[42:45], v27, s[12:13] nt
	global_load_dwordx4 v[20:23], v[24:25], off nt
	s_nop 0
	global_load_dwordx4 v[16:19], v[50:51], off offset:48 nt
	global_load_dwordx4 v[74:77], v46, s[12:13] nt
	global_load_dwordx4 v[24:27], v[50:51], off offset:32 nt
	global_load_dwordx4 v[28:31], v[50:51], off offset:16 nt
	v_or_b32_e32 v46, s10, v55
	v_lshlrev_b32_e32 v50, 1, v46
	v_mov_b32_e32 v51, v49
	v_lshl_add_u64 v[50:51], s[30:31], 0, v[50:51]
	s_mov_b64 s[12:13], 0x18700000
	v_or_b32_e32 v46, s0, v218
	v_lshl_add_u64 v[70:71], v[50:51], 0, s[12:13]
	v_lshlrev_b64 v[50:51], 12, v[46:47]
	v_lshl_add_u64 v[72:73], v[70:71], 0, v[50:51]
	v_or_b32_e32 v50, 16, v46
	v_mov_b32_e32 v51, v47
	v_lshlrev_b64 v[50:51], 12, v[50:51]
	v_lshl_add_u64 v[78:79], v[70:71], 0, v[50:51]
	v_or_b32_e32 v50, 32, v46
	v_mov_b32_e32 v51, v47
	v_lshlrev_b64 v[50:51], 12, v[50:51]
	v_lshl_add_u64 v[80:81], v[70:71], 0, v[50:51]
	v_or_b32_e32 v50, 48, v46
	v_mov_b32_e32 v51, v47
	v_lshlrev_b64 v[50:51], 12, v[50:51]
	v_lshl_add_u64 v[82:83], v[70:71], 0, v[50:51]
	v_or_b32_e32 v50, s10, v218
	v_mov_b32_e32 v51, v49
	v_lshlrev_b64 v[52:53], 2, v[50:51]
	v_lshl_add_u64 v[50:51], s[42:43], 0, v[52:53]
	global_load_dword v50, v[50:51], off nt
	v_or_b32_e32 v51, s9, v218
	v_lshl_add_u64 v[52:53], s[44:45], 0, v[52:53]
	v_lshlrev_b32_e32 v51, 2, v51
	global_load_dword v52, v[52:53], off nt
	s_nop 0
	global_load_dword v54, v51, s[48:49] nt
	global_load_dword v56, v51, s[48:49] offset:64 nt
	global_load_dword v58, v51, s[48:49] offset:128 nt
	global_load_dword v60, v51, s[48:49] offset:192 nt
	global_load_dword v62, v51, s[48:49] offset:256 nt
	global_load_dword v64, v51, s[48:49] offset:320 nt
	global_load_dword v66, v51, s[48:49] offset:384 nt
	global_load_dword v68, v51, s[48:49] offset:448 nt
	global_load_dwordx2 v[94:95], v[72:73], off nt
	global_load_dwordx2 v[92:93], v[78:79], off nt
	global_load_dwordx2 v[90:91], v[80:81], off nt
	global_load_dwordx2 v[88:89], v[82:83], off nt
	v_or_b32_e32 v51, 64, v218
	v_or_b32_e32 v72, s0, v51
	v_mov_b32_e32 v73, v47
	v_lshlrev_b64 v[72:73], 12, v[72:73]
	v_lshl_add_u64 v[78:79], v[70:71], 0, v[72:73]
	v_or_b32_e32 v72, 0x50, v46
	v_mov_b32_e32 v73, v47
	v_lshlrev_b64 v[72:73], 12, v[72:73]
	v_lshl_add_u64 v[82:83], v[70:71], 0, v[72:73]
	v_or_b32_e32 v72, 0x60, v46
	v_mov_b32_e32 v73, v47
	v_or_b32_e32 v46, 0x70, v46
	v_lshlrev_b64 v[72:73], 12, v[72:73]
	v_lshlrev_b64 v[46:47], 12, v[46:47]
	v_lshl_add_u64 v[84:85], v[70:71], 0, v[72:73]
	v_lshl_add_u64 v[46:47], v[70:71], 0, v[46:47]
	global_load_dwordx2 v[86:87], v[78:79], off nt
	global_load_dwordx2 v[80:81], v[82:83], off nt
	global_load_dwordx2 v[72:73], v[84:85], off nt
	global_load_dwordx2 v[70:71], v[46:47], off nt
	v_add_u32_e32 v46, 0, v222
	v_add_u32_e32 v112, v46, v223
	s_movk_i32 s0, 0x110
	v_lshrrev_b32_e32 v33, 4, v33
	v_or_b32_e32 v115, s9, v55
	s_lshr_b32 s9, s8, 1
	s_lshl_b32 s8, s8, 3
	s_and_b32 s13, s8, 0x400
	s_add_i32 s8, 0, 0x11000
	s_lshl_b32 s7, s4, 7
	s_lshr_b32 s12, s10, 6
	v_lshl_add_u32 v117, v32, 3, s8
	v_lshl_add_u32 v118, v211, 6, s8
	v_and_or_b32 v122, s9, 32, v219
	v_lshl_or_b32 v123, s4, 13, v96
	v_lshlrev_b32_e32 v32, 8, v32
	v_lshl_add_u32 v116, v211, 4, 0
	s_movk_i32 s3, 0x2000
	s_mov_b32 s14, 0x18f00000
	s_mov_b32 s15, 0x18f10000
	s_mov_b32 s16, 0x18f20000
	s_mov_b32 s17, 0x18f30000
	s_movk_i32 s18, 0x3c0
	s_movk_i32 s19, 0x1000
	s_movk_i32 s20, 0x3000
	s_waitcnt vmcnt(25)
; #define LAS __attribute__((address_space(3)))
; __device__ __forceinline__ void gmlp_phase(const Args& a, LAS unsigned char* lds, int bid) {
;     ...
;     GmIn cur; gm_load(a, g, blk0, cur);
;     {
;         const bf16_t* WM = (const bf16_t*)(a.ws + WS_WM) + (size_t)g * 128 * 128;
; #pragma unroll
;         for (int i = 0; i < 4; ++i) { const int c16 = tid + 512 * i; *(LAS u32x4*)(lds + GL_WM + (c16 >> 4) * 272 + (c16 & 15) * 16) = *(const u32x4*)(WM + (size_t)c16 * 8); }
;     }
;     const int c = g * 128 + 16 * w + fr, cc = g * 128 + 16 * w + 4 * fq;
;     const float lnw = a.ln_w[c], lnb = a.ln_b[c];
;     float bias[8];
; #pragma unroll
;     for (int it = 0; it < 8; ++it) bias[it] = a.b_s[g * 128 + 16 * it + fr];
;     for (int k = 0; k < 8; ++k) {
;         const size_t t0 = (size_t)(blk0 + 16 * k) * 128;
; #pragma unroll
;         for (int i = 0; i < 4; ++i) { const int c16 = tid + 512 * i; *(LAS u32x4*)(lds + GL_GV + (c16 >> 4) * 272 + (c16 & 15) * 16) = cur.gv[i]; }
;         {
;             float s1 = 0.f, s2 = 0.f;
; #pragma unroll
;             for (int q = 0; q < 4; ++q) { const f32x4 v = cur.st[q]; s1 += v[0] + v[2]; s2 += v[1] + v[3]; }
;             s1 += __shfl_xor(s1, 1); s1 += __shfl_xor(s1, 2); s2 += __shfl_xor(s2, 1); s2 += __shfl_xor(s2, 2);
;             const float mean = s1 * (1.0f / BW), var = s2 * (1.0f / BW) - mean * mean;
;             if ((tid & 3) == 0) MR[tid >> 2] = (f32x2){mean, __builtin_amdgcn_rsqf(var + EPS)};
;         }
;         u32x2 guz[8];
; #pragma unroll
;         for (int it = 0; it < 8; ++it) guz[it] = cur.guz[it];
;         __syncthreads();
;         if (k + 1 < 8) gm_load(a, g, blk0 + 16 * (k + 1), cur);
	ds_write_b128 v112, v[34:37]
	v_mad_u32_u24 v34, v97, s0, v46
	v_mul_u32_u24_e32 v37, 0x110, v33
	v_mad_u32_u24 v33, v33, s0, v46
	s_waitcnt vmcnt(24)
	ds_write_b128 v34, v[38:41]
	s_waitcnt vmcnt(23)
	ds_write_b128 v33, v[42:45]
	v_mad_u32_u24 v33, v48, s0, v46
	s_waitcnt vmcnt(20)
	ds_write_b128 v33, v[74:77]
	v_xor_b32_e32 v33, 1, v224
	v_cmp_lt_i32_e32 vcc, v33, v225
	v_mov_b32_e32 v35, v49
	v_lshlrev_b32_e32 v45, 4, v218
	v_cndmask_b32_e32 v33, v224, v33, vcc
	v_lshlrev_b32_e32 v113, 2, v33
	v_xor_b32_e32 v33, 2, v224
	v_cmp_lt_i32_e32 vcc, v33, v225
	v_mul_u32_u24_e32 v38, 0x110, v48
	v_lshlrev_b32_e32 v48, 12, v48
	v_cndmask_b32_e32 v33, v224, v33, vcc
	v_lshlrev_b32_e32 v114, 2, v33
	v_and_or_b32 v33, v158, 12, s11
	v_lshl_add_u32 v39, v33, 1, 0
	v_or_b32_e32 v33, 32, v219
	v_or_b32_e32 v34, v33, v220
	v_lshl_add_u32 v119, v33, 3, s8
	v_or_b32_e32 v33, 64, v219
	v_mul_u32_u24_e32 v41, 0x110, v34
	v_or_b32_e32 v34, v33, v220
	v_lshl_add_u32 v120, v33, 3, s8
	v_or_b32_e32 v33, 0x60, v219
	v_lshl_add_u32 v121, v33, 3, s8
	s_lshl_b64 s[8:9], s[4:5], 19
	v_mul_u32_u24_e32 v42, 0x110, v34
	v_or_b32_e32 v34, v33, v220
	s_add_u32 s10, s30, s8
	v_mul_u32_u24_e32 v43, 0x110, v34
	v_lshlrev_b32_e32 v34, 12, v218
	s_addc_u32 s11, s31, s9
	v_lshl_or_b32 v33, v216, 12, s8
	v_lshl_add_u64 v[74:75], s[10:11], 0, v[34:35]
	v_or3_b32 v34, v33, s6, v45
	v_mov_b32_e32 v35, s9
	v_lshl_or_b32 v33, v97, 12, s8
	v_lshl_add_u64 v[76:77], s[30:31], 0, v[34:35]
	v_or3_b32 v34, v33, s6, v45
	s_lshl_b64 s[4:5], s[4:5], 15
	v_mov_b32_e32 v33, v49
	v_lshl_add_u64 v[32:33], s[4:5], 0, v[32:33]
	v_lshl_or_b32 v32, v217, 6, v32
	v_lshl_add_u64 v[32:33], s[30:31], 0, v[32:33]
	s_mov_b64 s[4:5], 0x48b80020
	v_lshl_add_u64 v[82:83], v[32:33], 0, s[4:5]
	v_lshl_add_u64 v[32:33], s[8:9], 0, v[48:49]
	v_or3_b32 v32, v32, s6, v45
	v_mul_u32_u24_e32 v36, 0x110, v97
	v_mul_u32_u24_e32 v40, 0x110, v221
	v_mul_u32_u24_e32 v44, 0x110, v51
	v_lshl_add_u64 v[34:35], s[30:31], 0, v[34:35]
	s_mov_b64 s[10:11], 0x1cf00000
	v_lshl_add_u64 v[32:33], s[30:31], 0, v[32:33]
	v_cmp_eq_u32_e64 s[0:1], 0, v217
	s_waitcnt vmcnt(15)
	v_mov_b32_e32 v55, v54
	v_mov_b32_e32 v53, v52
	v_mov_b32_e32 v51, v50
	s_waitcnt vmcnt(14)
	v_mov_b32_e32 v57, v56
	s_waitcnt vmcnt(13)
	v_mov_b32_e32 v59, v58
	s_waitcnt vmcnt(12)
	v_mov_b32_e32 v61, v60
	s_waitcnt vmcnt(11)
	v_mov_b32_e32 v63, v62
	s_waitcnt vmcnt(10)
	v_mov_b32_e32 v65, v64
	s_waitcnt vmcnt(9)
	v_mov_b32_e32 v67, v66
	s_waitcnt vmcnt(8)
	v_mov_b32_e32 v69, v68
	v_lshl_add_u64 v[78:79], v[34:35], 0, s[10:11]
	v_lshl_add_u64 v[84:85], v[32:33], 0, s[10:11]
	s_mov_b64 s[4:5], 0
	v_add_u32_e32 v124, v46, v36
	v_add_u32_e32 v125, v46, v37
	v_add_u32_e32 v126, v46, v38
	s_mov_b32 s6, 0x3a000000
	v_add_u32_e32 v127, v39, v40
	v_add_u32_e32 v128, v39, v41
	v_add_u32_e32 v129, v39, v42
	v_add_u32_e32 v130, v39, v43
	v_add_u32_e32 v131, v116, v44
	s_mov_b64 s[8:9], 0x80000
	s_branch .LBB0_375
.LBB0_373:
	v_lshl_add_u64 v[8:9], v[76:77], 0, s[4:5]
	v_readfirstlane_b32 s10, v210
	v_add_co_u32_e32 v10, vcc, 0x1cf00000, v8
	s_lshr_b32 s10, s10, 2
	s_nop 0
	v_addc_co_u32_e32 v11, vcc, 0, v9, vcc
	v_add_co_u32_e32 v32, vcc, 0x1cf40000, v8
	s_and_b32 s10, s10, 0x3ffffff0
	v_lshl_add_u64 v[12:13], v[78:79], 0, s[4:5]
	v_addc_co_u32_e32 v33, vcc, 0, v9, vcc
	v_add_lshl_u32 v48, v115, s10, 1
	global_load_dwordx4 v[0:3], v[10:11], off nt
	global_load_dwordx4 v[4:7], v[12:13], off nt
	v_lshl_add_u64 v[34:35], v[84:85], 0, s[4:5]
	global_load_dwordx4 v[8:11], v[32:33], off nt
	global_load_dwordx4 v[12:15], v[34:35], off nt
	global_load_dwordx4 v[16:19], v[82:83], off offset:16 nt
	global_load_dwordx4 v[24:27], v[82:83], off nt
	global_load_dwordx4 v[28:31], v[82:83], off offset:-16 nt
	global_load_dwordx4 v[20:23], v[82:83], off offset:-32 nt
	v_lshl_add_u64 v[32:33], s[4:5], 0, v[48:49]
	v_lshl_add_u64 v[32:33], v[74:75], 0, v[32:33]
	v_add_co_u32_e32 v34, vcc, s14, v32
	s_nop 1
	v_addc_co_u32_e32 v35, vcc, 0, v33, vcc
	v_add_co_u32_e32 v36, vcc, s15, v32
	s_nop 1
	v_addc_co_u32_e32 v37, vcc, 0, v33, vcc
	v_add_co_u32_e32 v38, vcc, s16, v32
	s_nop 1
	v_addc_co_u32_e32 v39, vcc, 0, v33, vcc
	v_add_co_u32_e32 v40, vcc, s17, v32
	s_nop 1
	v_addc_co_u32_e32 v41, vcc, 0, v33, vcc
	global_load_dwordx2 v[96:97], v[34:35], off nt
	global_load_dwordx2 v[98:99], v[36:37], off nt
	global_load_dwordx2 v[100:101], v[38:39], off nt
	global_load_dwordx2 v[102:103], v[40:41], off nt
	v_add_co_u32_e32 v34, vcc, 0x18f40000, v32
	s_nop 1
	v_addc_co_u32_e32 v35, vcc, 0, v33, vcc
	v_add_co_u32_e32 v36, vcc, 0x18f50000, v32
	s_nop 1
	v_addc_co_u32_e32 v37, vcc, 0, v33, vcc
	v_add_co_u32_e32 v38, vcc, 0x18f60000, v32
	s_nop 1
	v_addc_co_u32_e32 v39, vcc, 0, v33, vcc
	v_add_co_u32_e32 v32, vcc, 0x18f70000, v32
	s_nop 1
	v_addc_co_u32_e32 v33, vcc, 0, v33, vcc
	global_load_dwordx2 v[104:105], v[34:35], off nt
	global_load_dwordx2 v[106:107], v[36:37], off nt
	global_load_dwordx2 v[108:109], v[38:39], off nt
	global_load_dwordx2 v[110:111], v[32:33], off nt

; __device__ __forceinline__ void phase5(const Args& a, int bid, int G) {
;     ...
;     for (int m = gw; m < T; m += NGW) {
;         const float tot = wave_sum(rsq[(size_t)m * 64 + lane]);
;         const float rstd = __builtin_amdgcn_rsqf(tot * (1.0f / DM) + EPS);
;         const u32x4* yr = (const u32x4*)(Y + (size_t)m * LDP) + lane;
;         f32x4* orow = (f32x4*)(a.out + (size_t)m * DM) + 2 * lane;
;         u32x4 v[8];
; #pragma unroll
;         for (int j = 0; j < 8; ++j) v[j] = yr[64 * j];
; #pragma unroll
;         for (int j = 0; j < 8; ++j) { const f32x4 w0 = *((const f32x4*)a.fin_w + 2 * lane + 128 * j), w1 = *((const f32x4*)a.fin_w + 2 * lane + 128 * j + 1);
;             orow[128 * j] = (f32x4){bflo(v[j].x) * rstd * w0[0], bfhi(v[j].x) * rstd * w0[1], bflo(v[j].y) * rstd * w0[2], bfhi(v[j].y) * rstd * w0[3]};
;             orow[128 * j + 1] = (f32x4){bflo(v[j].z) * rstd * w1[0], bfhi(v[j].z) * rstd * w1[1], bflo(v[j].w) * rstd * w1[2], bfhi(v[j].w) * rstd * w1[3]}; }
;     }
.LBB0_617:
	v_lshl_add_u64 v[0:1], s[30:31], 0, v[28:29]
	global_load_dwordx4 v[40:43], v[12:13], off offset:16 nt
	global_load_dwordx4 v[44:47], v[12:13], off nt
	global_load_dword v32, v[0:1], off nt
	v_lshl_add_u64 v[2:3], s[30:31], 0, v[30:31]
	v_add_co_u32_e32 v68, vcc, s1, v2
	s_add_i32 s8, s8, s0
	s_nop 0
	v_addc_co_u32_e32 v69, vcc, 0, v3, vcc
	v_add_co_u32_e32 v70, vcc, s9, v2
	v_lshl_add_u64 v[28:29], v[28:29], 0, s[4:5]
	s_nop 0
	v_addc_co_u32_e32 v71, vcc, 0, v3, vcc
	global_load_dwordx4 v[48:51], v[70:71], off offset:-4096 nt
	global_load_dwordx4 v[52:55], v[68:69], off offset:1024 nt
	global_load_dwordx4 v[56:59], v[68:69], off offset:2048 nt
	global_load_dwordx4 v[60:63], v[68:69], off offset:3072 nt
	global_load_dwordx4 v[64:67], v[70:71], off nt
	global_load_dwordx4 v[8:11], v[70:71], off offset:1024 nt
	global_load_dwordx4 v[4:7], v[70:71], off offset:2048 nt
	global_load_dwordx4 v[0:3], v[70:71], off offset:3072 nt
	v_lshl_add_u64 v[30:31], v[30:31], 0, s[6:7]
	s_cmpk_lt_i32 s8, 0x4000
	s_waitcnt vmcnt(0)
	ds_bpermute_b32 v72, v33, v32
	v_lshlrev_b32_e32 v68, 16, v48
	s_waitcnt lgkmcnt(0)
	v_add_f32_e32 v32, v32, v72
	ds_bpermute_b32 v72, v34, v32
	v_and_b32_e32 v69, 0xffff0000, v48
	v_lshlrev_b32_e32 v48, 16, v49
	v_and_b32_e32 v49, 0xffff0000, v49
	v_lshlrev_b32_e32 v70, 16, v50
	s_waitcnt lgkmcnt(0)
	v_add_f32_e32 v32, v32, v72
	ds_bpermute_b32 v72, v35, v32
	v_and_b32_e32 v71, 0xffff0000, v50
	v_lshlrev_b32_e32 v50, 16, v51
	v_and_b32_e32 v51, 0xffff0000, v51
	s_waitcnt lgkmcnt(0)
	v_add_f32_e32 v32, v32, v72
	ds_bpermute_b32 v72, v36, v32
	s_waitcnt lgkmcnt(0)
	v_add_f32_e32 v32, v32, v72
	ds_bpermute_b32 v72, v37, v32
	s_waitcnt lgkmcnt(0)
	v_add_f32_e32 v32, v32, v72
	ds_bpermute_b32 v72, v38, v32
	s_waitcnt lgkmcnt(0)
	v_add_f32_e32 v32, v32, v72
	v_fmamk_f32 v32, v32, 0x39800000, v39
	v_rsq_f32_e32 v32, v32
	s_nop 0
	v_pk_mul_f32 v[68:69], v[32:33], v[68:69] op_sel_hi:[0,1]
	v_pk_mul_f32 v[48:49], v[32:33], v[48:49] op_sel_hi:[0,1]
	v_pk_mul_f32 v[70:71], v[32:33], v[70:71] op_sel_hi:[0,1]
	v_pk_mul_f32 v[50:51], v[32:33], v[50:51] op_sel_hi:[0,1]
	v_pk_mul_f32 v[44:45], v[68:69], v[44:45]
	v_pk_mul_f32 v[46:47], v[48:49], v[46:47]
	v_pk_mul_f32 v[40:41], v[70:71], v[40:41]
	v_pk_mul_f32 v[42:43], v[50:51], v[42:43]
	global_store_dwordx4 v[26:27], v[44:47], off nt
	global_store_dwordx4 v[26:27], v[40:43], off offset:16 nt
	global_load_dwordx4 v[40:43], v[12:13], off offset:2048 nt
	s_nop 0
	global_load_dwordx4 v[44:47], v[12:13], off offset:2064 nt
	v_lshlrev_b32_e32 v48, 16, v52
	v_and_b32_e32 v49, 0xffff0000, v52
	v_lshlrev_b32_e32 v50, 16, v53
	v_and_b32_e32 v51, 0xffff0000, v53
	v_lshlrev_b32_e32 v52, 16, v54
	v_and_b32_e32 v53, 0xffff0000, v54
	v_lshlrev_b32_e32 v54, 16, v55
	v_and_b32_e32 v55, 0xffff0000, v55
	v_pk_mul_f32 v[48:49], v[32:33], v[48:49] op_sel_hi:[0,1]
	v_pk_mul_f32 v[50:51], v[32:33], v[50:51] op_sel_hi:[0,1]
	v_pk_mul_f32 v[52:53], v[32:33], v[52:53] op_sel_hi:[0,1]
	v_pk_mul_f32 v[54:55], v[32:33], v[54:55] op_sel_hi:[0,1]
	s_waitcnt vmcnt(1)
	v_pk_mul_f32 v[40:41], v[48:49], v[40:41]
	v_pk_mul_f32 v[42:43], v[50:51], v[42:43]
	s_waitcnt vmcnt(0)
	v_pk_mul_f32 v[44:45], v[52:53], v[44:45]
	v_pk_mul_f32 v[46:47], v[54:55], v[46:47]
	global_store_dwordx4 v[26:27], v[40:43], off offset:2048 nt
	global_store_dwordx4 v[26:27], v[44:47], off offset:2064 nt
	global_load_dwordx4 v[40:43], v[14:15], off nt
	s_nop 0
	global_load_dwordx4 v[44:47], v[14:15], off offset:16 nt
	v_add_co_u32_e32 v48, vcc, s10, v26
	v_lshlrev_b32_e32 v52, 16, v56
	s_nop 0
	v_addc_co_u32_e32 v49, vcc, 0, v27, vcc
	v_and_b32_e32 v53, 0xffff0000, v56
	v_lshlrev_b32_e32 v54, 16, v57
	v_and_b32_e32 v55, 0xffff0000, v57
	v_add_co_u32_e32 v50, vcc, s11, v26
	v_lshlrev_b32_e32 v56, 16, v58
	v_and_b32_e32 v57, 0xffff0000, v58
	v_lshlrev_b32_e32 v58, 16, v59
	v_and_b32_e32 v59, 0xffff0000, v59
	v_pk_mul_f32 v[52:53], v[32:33], v[52:53] op_sel_hi:[0,1]
	v_pk_mul_f32 v[54:55], v[32:33], v[54:55] op_sel_hi:[0,1]
	v_addc_co_u32_e32 v51, vcc, 0, v27, vcc
	v_pk_mul_f32 v[56:57], v[32:33], v[56:57] op_sel_hi:[0,1]
	v_pk_mul_f32 v[58:59], v[32:33], v[58:59] op_sel_hi:[0,1]
	s_waitcnt vmcnt(1)
	v_pk_mul_f32 v[40:41], v[52:53], v[40:41]
	v_pk_mul_f32 v[42:43], v[54:55], v[42:43]
	s_waitcnt vmcnt(0)
; __device__ __forceinline__ void phase5(const Args& a, int bid, int G) {
;     ...
;         for (int j = 0; j < 8; ++j) { const f32x4 w0 = *((const f32x4*)a.fin_w + 2 * lane + 128 * j), w1 = *((const f32x4*)a.fin_w + 2 * lane + 128 * j + 1);
;             orow[128 * j] = (f32x4){bflo(v[j].x) * rstd * w0[0], bfhi(v[j].x) * rstd * w0[1], bflo(v[j].y) * rstd * w0[2], bfhi(v[j].y) * rstd * w0[3]};
;             orow[128 * j + 1] = (f32x4){bflo(v[j].z) * rstd * w1[0], bfhi(v[j].z) * rstd * w1[1], bflo(v[j].w) * rstd * w1[2], bfhi(v[j].w) * rstd * w1[3]}; }
;     }
	v_pk_mul_f32 v[44:45], v[56:57], v[44:45]
	v_pk_mul_f32 v[46:47], v[58:59], v[46:47]
	global_store_dwordx4 v[50:51], v[40:43], off offset:-4096 nt
	global_store_dwordx4 v[48:49], v[44:47], off offset:16 nt
	global_load_dwordx4 v[40:43], v[16:17], off nt
	s_nop 0
	global_load_dwordx4 v[44:47], v[16:17], off offset:16 nt
	v_lshlrev_b32_e32 v52, 16, v60
	v_and_b32_e32 v53, 0xffff0000, v60
	v_lshlrev_b32_e32 v54, 16, v61
	v_and_b32_e32 v55, 0xffff0000, v61
	v_lshlrev_b32_e32 v56, 16, v62
	v_and_b32_e32 v57, 0xffff0000, v62
	v_lshlrev_b32_e32 v58, 16, v63
	v_and_b32_e32 v59, 0xffff0000, v63
	v_pk_mul_f32 v[52:53], v[32:33], v[52:53] op_sel_hi:[0,1]
	v_pk_mul_f32 v[54:55], v[32:33], v[54:55] op_sel_hi:[0,1]
	v_pk_mul_f32 v[56:57], v[32:33], v[56:57] op_sel_hi:[0,1]
	v_pk_mul_f32 v[58:59], v[32:33], v[58:59] op_sel_hi:[0,1]
	s_waitcnt vmcnt(1)
	v_pk_mul_f32 v[40:41], v[52:53], v[40:41]
	v_pk_mul_f32 v[42:43], v[54:55], v[42:43]
	s_waitcnt vmcnt(0)
	v_pk_mul_f32 v[44:45], v[56:57], v[44:45]
	v_pk_mul_f32 v[46:47], v[58:59], v[46:47]
	global_store_dwordx4 v[48:49], v[40:43], off offset:2048 nt
	global_store_dwordx4 v[48:49], v[44:47], off offset:2064 nt
	global_load_dwordx4 v[40:43], v[18:19], off nt
	s_nop 0
	global_load_dwordx4 v[44:47], v[18:19], off offset:16 nt
	v_lshlrev_b32_e32 v48, 16, v64
	v_and_b32_e32 v49, 0xffff0000, v64
	v_lshlrev_b32_e32 v52, 16, v65
	v_and_b32_e32 v53, 0xffff0000, v65
	v_lshlrev_b32_e32 v54, 16, v66
	v_and_b32_e32 v55, 0xffff0000, v66
	v_lshlrev_b32_e32 v56, 16, v67
	v_and_b32_e32 v57, 0xffff0000, v67
	v_pk_mul_f32 v[48:49], v[32:33], v[48:49] op_sel_hi:[0,1]
	v_pk_mul_f32 v[52:53], v[32:33], v[52:53] op_sel_hi:[0,1]
	v_pk_mul_f32 v[54:55], v[32:33], v[54:55] op_sel_hi:[0,1]
	v_pk_mul_f32 v[56:57], v[32:33], v[56:57] op_sel_hi:[0,1]
	s_waitcnt vmcnt(1)
	v_pk_mul_f32 v[40:41], v[48:49], v[40:41]
	v_pk_mul_f32 v[42:43], v[52:53], v[42:43]
	s_waitcnt vmcnt(0)
	v_pk_mul_f32 v[44:45], v[54:55], v[44:45]
	v_pk_mul_f32 v[46:47], v[56:57], v[46:47]
	global_store_dwordx4 v[50:51], v[40:43], off nt
	global_store_dwordx4 v[50:51], v[44:47], off offset:16 nt
	global_load_dwordx4 v[40:43], v[20:21], off nt
	s_nop 0
	global_load_dwordx4 v[44:47], v[20:21], off offset:16 nt
	v_lshlrev_b32_e32 v48, 16, v8
	v_and_b32_e32 v49, 0xffff0000, v8
	v_lshlrev_b32_e32 v8, 16, v9
	v_and_b32_e32 v9, 0xffff0000, v9
	v_lshlrev_b32_e32 v52, 16, v10
	v_and_b32_e32 v53, 0xffff0000, v10
	v_lshlrev_b32_e32 v10, 16, v11
	v_and_b32_e32 v11, 0xffff0000, v11
	v_pk_mul_f32 v[48:49], v[32:33], v[48:49] op_sel_hi:[0,1]
	v_pk_mul_f32 v[54:55], v[32:33], v[8:9] op_sel_hi:[0,1]
	v_pk_mul_f32 v[52:53], v[32:33], v[52:53] op_sel_hi:[0,1]
	v_pk_mul_f32 v[56:57], v[32:33], v[10:11] op_sel_hi:[0,1]
	s_waitcnt vmcnt(1)
	v_pk_mul_f32 v[8:9], v[48:49], v[40:41]
	v_pk_mul_f32 v[10:11], v[54:55], v[42:43]
	s_waitcnt vmcnt(0)
	v_pk_mul_f32 v[40:41], v[52:53], v[44:45]
	v_pk_mul_f32 v[42:43], v[56:57], v[46:47]
	global_store_dwordx4 v[50:51], v[8:11], off offset:2048 nt
	global_store_dwordx4 v[50:51], v[40:43], off offset:2064 nt
	global_load_dwordx4 v[8:11], v[22:23], off nt
	s_nop 0
	global_load_dwordx4 v[40:43], v[22:23], off offset:16 nt
	v_lshlrev_b32_e32 v46, 16, v4
	v_and_b32_e32 v47, 0xffff0000, v4
	v_lshlrev_b32_e32 v4, 16, v5
	v_and_b32_e32 v5, 0xffff0000, v5
	v_add_co_u32_e32 v44, vcc, s12, v26
	v_lshlrev_b32_e32 v48, 16, v6
	v_and_b32_e32 v49, 0xffff0000, v6
	v_lshlrev_b32_e32 v6, 16, v7
	v_and_b32_e32 v7, 0xffff0000, v7
	v_pk_mul_f32 v[46:47], v[32:33], v[46:47] op_sel_hi:[0,1]
	v_pk_mul_f32 v[50:51], v[32:33], v[4:5] op_sel_hi:[0,1]
	v_addc_co_u32_e32 v45, vcc, 0, v27, vcc
	v_pk_mul_f32 v[48:49], v[32:33], v[48:49] op_sel_hi:[0,1]
	v_pk_mul_f32 v[52:53], v[32:33], v[6:7] op_sel_hi:[0,1]
	v_lshl_add_u64 v[26:27], v[26:27], 0, s[2:3]
	s_waitcnt vmcnt(1)
	v_pk_mul_f32 v[4:5], v[46:47], v[8:9]
	v_pk_mul_f32 v[6:7], v[50:51], v[10:11]
	s_waitcnt vmcnt(0)
	v_pk_mul_f32 v[8:9], v[48:49], v[40:41]
	v_pk_mul_f32 v[10:11], v[52:53], v[42:43]
	global_store_dwordx4 v[44:45], v[4:7], off nt
	global_store_dwordx4 v[44:45], v[8:11], off offset:16 nt
	global_load_dwordx4 v[4:7], v[24:25], off nt
	s_nop 0
	global_load_dwordx4 v[8:11], v[24:25], off offset:16 nt
	v_lshlrev_b32_e32 v40, 16, v0
	v_and_b32_e32 v41, 0xffff0000, v0
	v_lshlrev_b32_e32 v0, 16, v1
	v_and_b32_e32 v1, 0xffff0000, v1
	v_lshlrev_b32_e32 v42, 16, v2
	v_and_b32_e32 v43, 0xffff0000, v2
	v_lshlrev_b32_e32 v2, 16, v3
	v_and_b32_e32 v3, 0xffff0000, v3
	v_pk_mul_f32 v[40:41], v[32:33], v[40:41] op_sel_hi:[0,1]
	v_pk_mul_f32 v[46:47], v[32:33], v[0:1] op_sel_hi:[0,1]
	v_pk_mul_f32 v[42:43], v[32:33], v[42:43] op_sel_hi:[0,1]
	v_pk_mul_f32 v[48:49], v[32:33], v[2:3] op_sel_hi:[0,1]
	s_waitcnt vmcnt(1)
	v_pk_mul_f32 v[0:1], v[40:41], v[4:5]
	v_pk_mul_f32 v[2:3], v[46:47], v[6:7]
	s_waitcnt vmcnt(0)
	v_pk_mul_f32 v[4:5], v[42:43], v[8:9]
	v_pk_mul_f32 v[6:7], v[48:49], v[10:11]
	global_store_dwordx4 v[44:45], v[0:3], off offset:2048 nt
	global_store_dwordx4 v[44:45], v[4:7], off offset:2064 nt
	s_cbranch_scc1 .LBB0_617
